# PH0: modulation GEMV rewritten with 56-deep load pipelining and the six silu loads issued together
# speedup vs baseline: 1.0081x; 1.0081x over previous
.LBB0_11:
	s_mul_hi_i32 s0, s15, 0x2aaaaaab
	s_lshr_b32 s1, s0, 31
	s_ashr_i32 s0, s0, 4
	s_add_i32 s1, s0, s1
	s_mul_i32 s0, s1, 0x60
	s_sub_i32 s0, s15, s0
	s_lshl_b32 s0, s0, 6
	s_add_i32 s6, s15, 0x5f
	s_mov_b64 s[82:83], s[50:51]
	s_cmpk_lt_u32 s6, 0xbf
	s_mov_b64 s[80:81], s[48:49]
	s_mov_b64 s[78:79], s[46:47]
	s_mov_b64 s[76:77], s[44:45]
	s_mov_b64 s[74:75], s[42:43]
	s_mov_b64 s[72:73], s[40:41]
	s_mov_b64 s[70:71], s[38:39]
	s_mov_b64 s[68:69], s[36:37]
	s_cselect_b64 s[6:7], -1, 0
	v_readlane_b32 s36, v255, 19
	v_readlane_b32 s16, v255, 40
	s_and_b64 s[10:11], s[6:7], exec
	v_readlane_b32 s46, v255, 29
	v_readlane_b32 s28, v255, 52
	v_readlane_b32 s47, v255, 30
	v_readlane_b32 s29, v255, 53
	s_cselect_b32 s10, s28, s46
	s_mul_i32 s16, s86, 0x300000
	v_add_u32_e32 v6, s0, v12
	s_cselect_b32 s11, s29, s47
	s_add_u32 s10, s10, s16
	v_ashrrev_i32_e32 v7, 31, v6
	s_addc_u32 s11, s11, s13
	v_mov_b32_e32 v4, 0
	v_lshlrev_b32_e32 v133, 2, v6
	v_lshl_add_u64 v[6:7], v[6:7], 2, s[10:11]
	s_mov_b32 s16, s14
	v_mov_b32_e32 v8, 0
	v_mov_b32_e32 v9, v4
	v_mov_b32_e32 v13, s14
	v_readlane_b32 s24, v255, 48
	v_readlane_b32 s25, v255, 49
	v_readlane_b32 s26, v255, 50
	v_readlane_b32 s27, v255, 51
	v_lshlrev_b32_e32 v196, 2, v1
	v_add_u32_e32 v197, 0x1000, v196
	s_nop 4
	global_load_dword v190, v196, s[26:27]
	global_load_dword v191, v196, s[26:27] offset:2048
	global_load_dword v192, v196, s[24:25]
	global_load_dword v193, v196, s[24:25] offset:2048
	global_load_dword v194, v197, s[24:25]
	global_load_dword v195, v197, s[24:25] offset:2048
	global_load_dword v134, v133, s[10:11]
	s_add_u32 s10, s10, 0x6000
	s_addc_u32 s11, s11, 0
	global_load_dword v135, v133, s[10:11]
	s_add_u32 s10, s10, 0x6000
	s_addc_u32 s11, s11, 0
	global_load_dword v136, v133, s[10:11]
	s_add_u32 s10, s10, 0x6000
	s_addc_u32 s11, s11, 0
	global_load_dword v137, v133, s[10:11]
	s_add_u32 s10, s10, 0x6000
	s_addc_u32 s11, s11, 0
	global_load_dword v138, v133, s[10:11]
	s_add_u32 s10, s10, 0x6000
	s_addc_u32 s11, s11, 0
	global_load_dword v139, v133, s[10:11]
	s_add_u32 s10, s10, 0x6000
	s_addc_u32 s11, s11, 0
	global_load_dword v140, v133, s[10:11]
	s_add_u32 s10, s10, 0x6000
	s_addc_u32 s11, s11, 0
	global_load_dword v141, v133, s[10:11]
	s_add_u32 s10, s10, 0x6000
	s_addc_u32 s11, s11, 0
	global_load_dword v142, v133, s[10:11]
	s_add_u32 s10, s10, 0x6000
	s_addc_u32 s11, s11, 0
	global_load_dword v143, v133, s[10:11]
	s_add_u32 s10, s10, 0x6000
	s_addc_u32 s11, s11, 0
	global_load_dword v144, v133, s[10:11]
	s_add_u32 s10, s10, 0x6000
	s_addc_u32 s11, s11, 0
	global_load_dword v145, v133, s[10:11]
	s_add_u32 s10, s10, 0x6000
	s_addc_u32 s11, s11, 0
	global_load_dword v146, v133, s[10:11]
	s_add_u32 s10, s10, 0x6000
	s_addc_u32 s11, s11, 0
	global_load_dword v147, v133, s[10:11]
	s_add_u32 s10, s10, 0x6000
	s_addc_u32 s11, s11, 0
	global_load_dword v148, v133, s[10:11]
	s_add_u32 s10, s10, 0x6000
	s_addc_u32 s11, s11, 0
	global_load_dword v149, v133, s[10:11]
	s_add_u32 s10, s10, 0x6000
	s_addc_u32 s11, s11, 0
	global_load_dword v150, v133, s[10:11]
	s_add_u32 s10, s10, 0x6000
	s_addc_u32 s11, s11, 0
	global_load_dword v151, v133, s[10:11]
	s_add_u32 s10, s10, 0x6000
	s_addc_u32 s11, s11, 0
	global_load_dword v152, v133, s[10:11]
	s_add_u32 s10, s10, 0x6000
	s_addc_u32 s11, s11, 0
	global_load_dword v153, v133, s[10:11]
	s_add_u32 s10, s10, 0x6000
	s_addc_u32 s11, s11, 0
	global_load_dword v154, v133, s[10:11]
	s_add_u32 s10, s10, 0x6000
	s_addc_u32 s11, s11, 0
	global_load_dword v155, v133, s[10:11]
	s_add_u32 s10, s10, 0x6000
	s_addc_u32 s11, s11, 0
	global_load_dword v156, v133, s[10:11]
	s_add_u32 s10, s10, 0x6000
	s_addc_u32 s11, s11, 0
	global_load_dword v157, v133, s[10:11]
	s_add_u32 s10, s10, 0x6000
	s_addc_u32 s11, s11, 0
	global_load_dword v158, v133, s[10:11]
	s_add_u32 s10, s10, 0x6000
	s_addc_u32 s11, s11, 0
	global_load_dword v159, v133, s[10:11]
	s_add_u32 s10, s10, 0x6000
	s_addc_u32 s11, s11, 0
	global_load_dword v160, v133, s[10:11]
	s_add_u32 s10, s10, 0x6000
	s_addc_u32 s11, s11, 0
	global_load_dword v161, v133, s[10:11]
	s_add_u32 s10, s10, 0x6000
	s_addc_u32 s11, s11, 0
	global_load_dword v162, v133, s[10:11]
	s_add_u32 s10, s10, 0x6000
	s_addc_u32 s11, s11, 0
	global_load_dword v163, v133, s[10:11]
	s_add_u32 s10, s10, 0x6000
	s_addc_u32 s11, s11, 0
	global_load_dword v164, v133, s[10:11]
	s_add_u32 s10, s10, 0x6000
	s_addc_u32 s11, s11, 0
	global_load_dword v165, v133, s[10:11]
	s_add_u32 s10, s10, 0x6000
	s_addc_u32 s11, s11, 0
	global_load_dword v166, v133, s[10:11]
	s_add_u32 s10, s10, 0x6000
	s_addc_u32 s11, s11, 0
	global_load_dword v167, v133, s[10:11]
	s_add_u32 s10, s10, 0x6000
	s_addc_u32 s11, s11, 0
	global_load_dword v168, v133, s[10:11]
	s_add_u32 s10, s10, 0x6000
	s_addc_u32 s11, s11, 0
	global_load_dword v169, v133, s[10:11]
	s_add_u32 s10, s10, 0x6000
	s_addc_u32 s11, s11, 0
	global_load_dword v170, v133, s[10:11]
	s_add_u32 s10, s10, 0x6000
	s_addc_u32 s11, s11, 0
	global_load_dword v171, v133, s[10:11]
	s_add_u32 s10, s10, 0x6000
	s_addc_u32 s11, s11, 0
	global_load_dword v172, v133, s[10:11]
	s_add_u32 s10, s10, 0x6000
	s_addc_u32 s11, s11, 0
	global_load_dword v173, v133, s[10:11]
	s_add_u32 s10, s10, 0x6000
	s_addc_u32 s11, s11, 0
	global_load_dword v174, v133, s[10:11]
	s_add_u32 s10, s10, 0x6000
	s_addc_u32 s11, s11, 0
	global_load_dword v175, v133, s[10:11]
	s_add_u32 s10, s10, 0x6000
	s_addc_u32 s11, s11, 0
	global_load_dword v176, v133, s[10:11]
	s_add_u32 s10, s10, 0x6000
	s_addc_u32 s11, s11, 0
	global_load_dword v177, v133, s[10:11]
	s_add_u32 s10, s10, 0x6000
	s_addc_u32 s11, s11, 0
	global_load_dword v178, v133, s[10:11]
	s_add_u32 s10, s10, 0x6000
	s_addc_u32 s11, s11, 0
	global_load_dword v179, v133, s[10:11]
	s_add_u32 s10, s10, 0x6000
	s_addc_u32 s11, s11, 0
	global_load_dword v180, v133, s[10:11]
	s_add_u32 s10, s10, 0x6000
	s_addc_u32 s11, s11, 0
	global_load_dword v181, v133, s[10:11]
	s_add_u32 s10, s10, 0x6000
	s_addc_u32 s11, s11, 0
	global_load_dword v182, v133, s[10:11]
	s_add_u32 s10, s10, 0x6000
	s_addc_u32 s11, s11, 0
	global_load_dword v183, v133, s[10:11]
	s_add_u32 s10, s10, 0x6000
	s_addc_u32 s11, s11, 0
	global_load_dword v184, v133, s[10:11]
	s_add_u32 s10, s10, 0x6000
	s_addc_u32 s11, s11, 0
	global_load_dword v185, v133, s[10:11]
	s_add_u32 s10, s10, 0x6000
	s_addc_u32 s11, s11, 0
	global_load_dword v186, v133, s[10:11]
	s_add_u32 s10, s10, 0x6000
	s_addc_u32 s11, s11, 0
	global_load_dword v187, v133, s[10:11]
	s_add_u32 s10, s10, 0x6000
	s_addc_u32 s11, s11, 0
	global_load_dword v188, v133, s[10:11]
	s_add_u32 s10, s10, 0x6000
	s_addc_u32 s11, s11, 0
	global_load_dword v189, v133, s[10:11]
	s_add_u32 s10, s10, 0x6000
	s_addc_u32 s11, s11, 0
	s_waitcnt vmcnt(61)
	v_mul_f32_e32 v14, 0xbfb8aa3b, v190
	v_exp_f32_e32 v14, v14
	s_nop 0
	v_add_f32_e32 v14, 1.0, v14
	v_div_scale_f32 v15, s[16:17], v14, v14, v190
	v_rcp_f32_e32 v16, v15
	v_div_scale_f32 v17, vcc, v190, v14, v190
	v_fma_f32 v18, -v15, v16, 1.0
	v_fmac_f32_e32 v16, v18, v16
	v_mul_f32_e32 v18, v17, v16
	v_fma_f32 v19, -v15, v18, v17
	v_fmac_f32_e32 v18, v19, v16
	v_fma_f32 v15, -v15, v18, v17
	v_div_fmas_f32 v15, v15, v16, v18
	v_div_fixup_f32 v15, v15, v14, v190
	ds_write_b32 v10, v15 offset:0
	s_waitcnt vmcnt(60)
	v_mul_f32_e32 v14, 0xbfb8aa3b, v191
	v_exp_f32_e32 v14, v14
	s_nop 0
	v_add_f32_e32 v14, 1.0, v14
	v_div_scale_f32 v15, s[16:17], v14, v14, v191
	v_rcp_f32_e32 v16, v15
	v_div_scale_f32 v17, vcc, v191, v14, v191
	v_fma_f32 v18, -v15, v16, 1.0
	v_fmac_f32_e32 v16, v18, v16
	v_mul_f32_e32 v18, v17, v16
	v_fma_f32 v19, -v15, v18, v17
	v_fmac_f32_e32 v18, v19, v16
	v_fma_f32 v15, -v15, v18, v17
	v_div_fmas_f32 v15, v15, v16, v18
	v_div_fixup_f32 v15, v15, v14, v191
	ds_write_b32 v10, v15 offset:2048
	s_waitcnt vmcnt(59)
	v_mul_f32_e32 v14, 0xbfb8aa3b, v192
	v_exp_f32_e32 v14, v14
	s_nop 0
	v_add_f32_e32 v14, 1.0, v14
	v_div_scale_f32 v15, s[16:17], v14, v14, v192
	v_rcp_f32_e32 v16, v15
	v_div_scale_f32 v17, vcc, v192, v14, v192
	v_fma_f32 v18, -v15, v16, 1.0
	v_fmac_f32_e32 v16, v18, v16
	v_mul_f32_e32 v18, v17, v16
	v_fma_f32 v19, -v15, v18, v17
	v_fmac_f32_e32 v18, v19, v16
	v_fma_f32 v15, -v15, v18, v17
	v_div_fmas_f32 v15, v15, v16, v18
	v_div_fixup_f32 v15, v15, v14, v192
	ds_write_b32 v10, v15 offset:4096
	s_waitcnt vmcnt(58)
	v_mul_f32_e32 v14, 0xbfb8aa3b, v193
	v_exp_f32_e32 v14, v14
	s_nop 0
	v_add_f32_e32 v14, 1.0, v14
	v_div_scale_f32 v15, s[16:17], v14, v14, v193
	v_rcp_f32_e32 v16, v15
	v_div_scale_f32 v17, vcc, v193, v14, v193
	v_fma_f32 v18, -v15, v16, 1.0
	v_fmac_f32_e32 v16, v18, v16
	v_mul_f32_e32 v18, v17, v16
	v_fma_f32 v19, -v15, v18, v17
	v_fmac_f32_e32 v18, v19, v16
	v_fma_f32 v15, -v15, v18, v17
	v_div_fmas_f32 v15, v15, v16, v18
	v_div_fixup_f32 v15, v15, v14, v193
	ds_write_b32 v10, v15 offset:6144
	s_waitcnt vmcnt(57)
	v_mul_f32_e32 v14, 0xbfb8aa3b, v194
	v_exp_f32_e32 v14, v14
	s_nop 0
	v_add_f32_e32 v14, 1.0, v14
	v_div_scale_f32 v15, s[16:17], v14, v14, v194
	v_rcp_f32_e32 v16, v15
	v_div_scale_f32 v17, vcc, v194, v14, v194
	v_fma_f32 v18, -v15, v16, 1.0
	v_fmac_f32_e32 v16, v18, v16
	v_mul_f32_e32 v18, v17, v16
	v_fma_f32 v19, -v15, v18, v17
	v_fmac_f32_e32 v18, v19, v16
	v_fma_f32 v15, -v15, v18, v17
	v_div_fmas_f32 v15, v15, v16, v18
	v_div_fixup_f32 v15, v15, v14, v194
	ds_write_b32 v10, v15 offset:8192
	s_waitcnt vmcnt(56)
	v_mul_f32_e32 v14, 0xbfb8aa3b, v195
	v_exp_f32_e32 v14, v14
	s_nop 0
	v_add_f32_e32 v14, 1.0, v14
	v_div_scale_f32 v15, s[16:17], v14, v14, v195
	v_rcp_f32_e32 v16, v15
	v_div_scale_f32 v17, vcc, v195, v14, v195
	v_fma_f32 v18, -v15, v16, 1.0
	v_fmac_f32_e32 v16, v18, v16
	v_mul_f32_e32 v18, v17, v16
	v_fma_f32 v19, -v15, v18, v17
	v_fmac_f32_e32 v18, v19, v16
	v_fma_f32 v15, -v15, v18, v17
	v_div_fmas_f32 v15, v15, v16, v18
	v_div_fixup_f32 v15, v15, v14, v195
	ds_write_b32 v10, v15 offset:10240
	s_waitcnt lgkmcnt(0)
	s_barrier
	v_readlane_b32 s37, v255, 20
	v_readlane_b32 s38, v255, 21
	v_readlane_b32 s39, v255, 22
	v_readlane_b32 s40, v255, 23
	v_readlane_b32 s41, v255, 24
	v_readlane_b32 s42, v255, 25
	v_readlane_b32 s43, v255, 26
	v_readlane_b32 s44, v255, 27
	v_readlane_b32 s45, v255, 28
	v_readlane_b32 s48, v255, 31
	v_readlane_b32 s49, v255, 32
	v_readlane_b32 s50, v255, 33
	v_readlane_b32 s51, v255, 34
	v_readlane_b32 s17, v255, 41
	v_readlane_b32 s18, v255, 42
	v_readlane_b32 s19, v255, 43
	v_readlane_b32 s20, v255, 44
	v_readlane_b32 s21, v255, 45
	v_readlane_b32 s22, v255, 46
	v_readlane_b32 s23, v255, 47
	v_readlane_b32 s24, v255, 48
	v_readlane_b32 s25, v255, 49
	v_readlane_b32 s26, v255, 50
	v_readlane_b32 s27, v255, 51
	v_readlane_b32 s30, v255, 54
	v_readlane_b32 s31, v255, 55
	ds_read_b128 v[14:17], v13 offset:0
	ds_read_b128 v[18:21], v13 offset:16
	ds_read_b128 v[22:25], v13 offset:4096
	ds_read_b128 v[26:29], v13 offset:4112
	ds_read_b128 v[30:33], v13 offset:8192
	ds_read_b128 v[34:37], v13 offset:8208
	s_waitcnt vmcnt(48)
	s_waitcnt lgkmcnt(0)
	v_fmac_f32_e32 v8, v134, v14
	v_fmac_f32_e32 v9, v134, v22
	v_fmac_f32_e32 v4, v134, v30
	v_fmac_f32_e32 v8, v135, v15
	v_fmac_f32_e32 v9, v135, v23
	v_fmac_f32_e32 v4, v135, v31
	v_fmac_f32_e32 v8, v136, v16
	v_fmac_f32_e32 v9, v136, v24
	v_fmac_f32_e32 v4, v136, v32
	v_fmac_f32_e32 v8, v137, v17
	v_fmac_f32_e32 v9, v137, v25
	v_fmac_f32_e32 v4, v137, v33
	v_fmac_f32_e32 v8, v138, v18
	v_fmac_f32_e32 v9, v138, v26
	v_fmac_f32_e32 v4, v138, v34
	v_fmac_f32_e32 v8, v139, v19
	v_fmac_f32_e32 v9, v139, v27
	v_fmac_f32_e32 v4, v139, v35
	v_fmac_f32_e32 v8, v140, v20
	v_fmac_f32_e32 v9, v140, v28
	v_fmac_f32_e32 v4, v140, v36
	v_fmac_f32_e32 v8, v141, v21
	v_fmac_f32_e32 v9, v141, v29
	v_fmac_f32_e32 v4, v141, v37
	global_load_dword v134, v133, s[10:11]
	s_add_u32 s10, s10, 0x6000
	s_addc_u32 s11, s11, 0
	global_load_dword v135, v133, s[10:11]
	s_add_u32 s10, s10, 0x6000
	s_addc_u32 s11, s11, 0
	global_load_dword v136, v133, s[10:11]
	s_add_u32 s10, s10, 0x6000
	s_addc_u32 s11, s11, 0
	global_load_dword v137, v133, s[10:11]
	s_add_u32 s10, s10, 0x6000
	s_addc_u32 s11, s11, 0
	global_load_dword v138, v133, s[10:11]
	s_add_u32 s10, s10, 0x6000
	s_addc_u32 s11, s11, 0
	global_load_dword v139, v133, s[10:11]
	s_add_u32 s10, s10, 0x6000
	s_addc_u32 s11, s11, 0
	global_load_dword v140, v133, s[10:11]
	s_add_u32 s10, s10, 0x6000
	s_addc_u32 s11, s11, 0
	global_load_dword v141, v133, s[10:11]
	s_add_u32 s10, s10, 0x6000
	s_addc_u32 s11, s11, 0
	ds_read_b128 v[14:17], v13 offset:32
	ds_read_b128 v[18:21], v13 offset:48
	ds_read_b128 v[22:25], v13 offset:4128
	ds_read_b128 v[26:29], v13 offset:4144
	ds_read_b128 v[30:33], v13 offset:8224
	ds_read_b128 v[34:37], v13 offset:8240
	s_waitcnt vmcnt(48)
	s_waitcnt lgkmcnt(0)
	v_fmac_f32_e32 v8, v142, v14
	v_fmac_f32_e32 v9, v142, v22
	v_fmac_f32_e32 v4, v142, v30
	v_fmac_f32_e32 v8, v143, v15
	v_fmac_f32_e32 v9, v143, v23
	v_fmac_f32_e32 v4, v143, v31
	v_fmac_f32_e32 v8, v144, v16
	v_fmac_f32_e32 v9, v144, v24
	v_fmac_f32_e32 v4, v144, v32
	v_fmac_f32_e32 v8, v145, v17
	v_fmac_f32_e32 v9, v145, v25
	v_fmac_f32_e32 v4, v145, v33
	v_fmac_f32_e32 v8, v146, v18
	v_fmac_f32_e32 v9, v146, v26
	v_fmac_f32_e32 v4, v146, v34
	v_fmac_f32_e32 v8, v147, v19
	v_fmac_f32_e32 v9, v147, v27
	v_fmac_f32_e32 v4, v147, v35
	v_fmac_f32_e32 v8, v148, v20
	v_fmac_f32_e32 v9, v148, v28
	v_fmac_f32_e32 v4, v148, v36
	v_fmac_f32_e32 v8, v149, v21
	v_fmac_f32_e32 v9, v149, v29
	v_fmac_f32_e32 v4, v149, v37
	global_load_dword v142, v133, s[10:11]
	s_add_u32 s10, s10, 0x6000
	s_addc_u32 s11, s11, 0
	global_load_dword v143, v133, s[10:11]
	s_add_u32 s10, s10, 0x6000
	s_addc_u32 s11, s11, 0
	global_load_dword v144, v133, s[10:11]
	s_add_u32 s10, s10, 0x6000
	s_addc_u32 s11, s11, 0
	global_load_dword v145, v133, s[10:11]
	s_add_u32 s10, s10, 0x6000
	s_addc_u32 s11, s11, 0
	global_load_dword v146, v133, s[10:11]
	s_add_u32 s10, s10, 0x6000
	s_addc_u32 s11, s11, 0
	global_load_dword v147, v133, s[10:11]
	s_add_u32 s10, s10, 0x6000
	s_addc_u32 s11, s11, 0
	global_load_dword v148, v133, s[10:11]
	s_add_u32 s10, s10, 0x6000
	s_addc_u32 s11, s11, 0
	global_load_dword v149, v133, s[10:11]
	s_add_u32 s10, s10, 0x6000
	s_addc_u32 s11, s11, 0
	ds_read_b128 v[14:17], v13 offset:64
	ds_read_b128 v[18:21], v13 offset:80
	ds_read_b128 v[22:25], v13 offset:4160
	ds_read_b128 v[26:29], v13 offset:4176
	ds_read_b128 v[30:33], v13 offset:8256
	ds_read_b128 v[34:37], v13 offset:8272
	s_waitcnt vmcnt(48)
	s_waitcnt lgkmcnt(0)
	v_fmac_f32_e32 v8, v150, v14
	v_fmac_f32_e32 v9, v150, v22
	v_fmac_f32_e32 v4, v150, v30
	v_fmac_f32_e32 v8, v151, v15
	v_fmac_f32_e32 v9, v151, v23
	v_fmac_f32_e32 v4, v151, v31
	v_fmac_f32_e32 v8, v152, v16
	v_fmac_f32_e32 v9, v152, v24
	v_fmac_f32_e32 v4, v152, v32
	v_fmac_f32_e32 v8, v153, v17
	v_fmac_f32_e32 v9, v153, v25
	v_fmac_f32_e32 v4, v153, v33
	v_fmac_f32_e32 v8, v154, v18
	v_fmac_f32_e32 v9, v154, v26
	v_fmac_f32_e32 v4, v154, v34
	v_fmac_f32_e32 v8, v155, v19
	v_fmac_f32_e32 v9, v155, v27
	v_fmac_f32_e32 v4, v155, v35
	v_fmac_f32_e32 v8, v156, v20
	v_fmac_f32_e32 v9, v156, v28
	v_fmac_f32_e32 v4, v156, v36
	v_fmac_f32_e32 v8, v157, v21
	v_fmac_f32_e32 v9, v157, v29
	v_fmac_f32_e32 v4, v157, v37
	global_load_dword v150, v133, s[10:11]
	s_add_u32 s10, s10, 0x6000
	s_addc_u32 s11, s11, 0
	global_load_dword v151, v133, s[10:11]
	s_add_u32 s10, s10, 0x6000
	s_addc_u32 s11, s11, 0
	global_load_dword v152, v133, s[10:11]
	s_add_u32 s10, s10, 0x6000
	s_addc_u32 s11, s11, 0
	global_load_dword v153, v133, s[10:11]
	s_add_u32 s10, s10, 0x6000
	s_addc_u32 s11, s11, 0
	global_load_dword v154, v133, s[10:11]
	s_add_u32 s10, s10, 0x6000
	s_addc_u32 s11, s11, 0
	global_load_dword v155, v133, s[10:11]
	s_add_u32 s10, s10, 0x6000
	s_addc_u32 s11, s11, 0
	global_load_dword v156, v133, s[10:11]
	s_add_u32 s10, s10, 0x6000
	s_addc_u32 s11, s11, 0
	global_load_dword v157, v133, s[10:11]
	s_add_u32 s10, s10, 0x6000
	s_addc_u32 s11, s11, 0
	ds_read_b128 v[14:17], v13 offset:96
	ds_read_b128 v[18:21], v13 offset:112
	ds_read_b128 v[22:25], v13 offset:4192
	ds_read_b128 v[26:29], v13 offset:4208
	ds_read_b128 v[30:33], v13 offset:8288
	ds_read_b128 v[34:37], v13 offset:8304
	s_waitcnt vmcnt(48)
	s_waitcnt lgkmcnt(0)
	v_fmac_f32_e32 v8, v158, v14
	v_fmac_f32_e32 v9, v158, v22
	v_fmac_f32_e32 v4, v158, v30
	v_fmac_f32_e32 v8, v159, v15
	v_fmac_f32_e32 v9, v159, v23
	v_fmac_f32_e32 v4, v159, v31
	v_fmac_f32_e32 v8, v160, v16
	v_fmac_f32_e32 v9, v160, v24
	v_fmac_f32_e32 v4, v160, v32
	v_fmac_f32_e32 v8, v161, v17
	v_fmac_f32_e32 v9, v161, v25
	v_fmac_f32_e32 v4, v161, v33
	v_fmac_f32_e32 v8, v162, v18
	v_fmac_f32_e32 v9, v162, v26
	v_fmac_f32_e32 v4, v162, v34
	v_fmac_f32_e32 v8, v163, v19
	v_fmac_f32_e32 v9, v163, v27
	v_fmac_f32_e32 v4, v163, v35
	v_fmac_f32_e32 v8, v164, v20
	v_fmac_f32_e32 v9, v164, v28
	v_fmac_f32_e32 v4, v164, v36
	v_fmac_f32_e32 v8, v165, v21
	v_fmac_f32_e32 v9, v165, v29
	v_fmac_f32_e32 v4, v165, v37
	global_load_dword v158, v133, s[10:11]
	s_add_u32 s10, s10, 0x6000
	s_addc_u32 s11, s11, 0
	global_load_dword v159, v133, s[10:11]
	s_add_u32 s10, s10, 0x6000
	s_addc_u32 s11, s11, 0
	global_load_dword v160, v133, s[10:11]
	s_add_u32 s10, s10, 0x6000
	s_addc_u32 s11, s11, 0
	global_load_dword v161, v133, s[10:11]
	s_add_u32 s10, s10, 0x6000
	s_addc_u32 s11, s11, 0
	global_load_dword v162, v133, s[10:11]
	s_add_u32 s10, s10, 0x6000
	s_addc_u32 s11, s11, 0
	global_load_dword v163, v133, s[10:11]
	s_add_u32 s10, s10, 0x6000
	s_addc_u32 s11, s11, 0
	global_load_dword v164, v133, s[10:11]
	s_add_u32 s10, s10, 0x6000
	s_addc_u32 s11, s11, 0
	global_load_dword v165, v133, s[10:11]
	s_add_u32 s10, s10, 0x6000
	s_addc_u32 s11, s11, 0
	ds_read_b128 v[14:17], v13 offset:128
	ds_read_b128 v[18:21], v13 offset:144
	ds_read_b128 v[22:25], v13 offset:4224
	ds_read_b128 v[26:29], v13 offset:4240
	ds_read_b128 v[30:33], v13 offset:8320
	ds_read_b128 v[34:37], v13 offset:8336
	s_waitcnt vmcnt(48)
	s_waitcnt lgkmcnt(0)
	v_fmac_f32_e32 v8, v166, v14
	v_fmac_f32_e32 v9, v166, v22
	v_fmac_f32_e32 v4, v166, v30
	v_fmac_f32_e32 v8, v167, v15
	v_fmac_f32_e32 v9, v167, v23
	v_fmac_f32_e32 v4, v167, v31
	v_fmac_f32_e32 v8, v168, v16
	v_fmac_f32_e32 v9, v168, v24
	v_fmac_f32_e32 v4, v168, v32
	v_fmac_f32_e32 v8, v169, v17
	v_fmac_f32_e32 v9, v169, v25
	v_fmac_f32_e32 v4, v169, v33
	v_fmac_f32_e32 v8, v170, v18
	v_fmac_f32_e32 v9, v170, v26
	v_fmac_f32_e32 v4, v170, v34
	v_fmac_f32_e32 v8, v171, v19
	v_fmac_f32_e32 v9, v171, v27
	v_fmac_f32_e32 v4, v171, v35
	v_fmac_f32_e32 v8, v172, v20
	v_fmac_f32_e32 v9, v172, v28
	v_fmac_f32_e32 v4, v172, v36
	v_fmac_f32_e32 v8, v173, v21
	v_fmac_f32_e32 v9, v173, v29
	v_fmac_f32_e32 v4, v173, v37
	global_load_dword v166, v133, s[10:11]
	s_add_u32 s10, s10, 0x6000
	s_addc_u32 s11, s11, 0
	global_load_dword v167, v133, s[10:11]
	s_add_u32 s10, s10, 0x6000
	s_addc_u32 s11, s11, 0
	global_load_dword v168, v133, s[10:11]
	s_add_u32 s10, s10, 0x6000
	s_addc_u32 s11, s11, 0
	global_load_dword v169, v133, s[10:11]
	s_add_u32 s10, s10, 0x6000
	s_addc_u32 s11, s11, 0
	global_load_dword v170, v133, s[10:11]
	s_add_u32 s10, s10, 0x6000
	s_addc_u32 s11, s11, 0
	global_load_dword v171, v133, s[10:11]
	s_add_u32 s10, s10, 0x6000
	s_addc_u32 s11, s11, 0
	global_load_dword v172, v133, s[10:11]
	s_add_u32 s10, s10, 0x6000
	s_addc_u32 s11, s11, 0
	global_load_dword v173, v133, s[10:11]
	s_add_u32 s10, s10, 0x6000
	s_addc_u32 s11, s11, 0
	ds_read_b128 v[14:17], v13 offset:160
	ds_read_b128 v[18:21], v13 offset:176
	ds_read_b128 v[22:25], v13 offset:4256
	ds_read_b128 v[26:29], v13 offset:4272
	ds_read_b128 v[30:33], v13 offset:8352
	ds_read_b128 v[34:37], v13 offset:8368
	s_waitcnt vmcnt(48)
	s_waitcnt lgkmcnt(0)
	v_fmac_f32_e32 v8, v174, v14
	v_fmac_f32_e32 v9, v174, v22
	v_fmac_f32_e32 v4, v174, v30
	v_fmac_f32_e32 v8, v175, v15
	v_fmac_f32_e32 v9, v175, v23
	v_fmac_f32_e32 v4, v175, v31
	v_fmac_f32_e32 v8, v176, v16
	v_fmac_f32_e32 v9, v176, v24
	v_fmac_f32_e32 v4, v176, v32
	v_fmac_f32_e32 v8, v177, v17
	v_fmac_f32_e32 v9, v177, v25
	v_fmac_f32_e32 v4, v177, v33
	v_fmac_f32_e32 v8, v178, v18
	v_fmac_f32_e32 v9, v178, v26
	v_fmac_f32_e32 v4, v178, v34
	v_fmac_f32_e32 v8, v179, v19
	v_fmac_f32_e32 v9, v179, v27
	v_fmac_f32_e32 v4, v179, v35
	v_fmac_f32_e32 v8, v180, v20
	v_fmac_f32_e32 v9, v180, v28
	v_fmac_f32_e32 v4, v180, v36
	v_fmac_f32_e32 v8, v181, v21
	v_fmac_f32_e32 v9, v181, v29
	v_fmac_f32_e32 v4, v181, v37
	global_load_dword v174, v133, s[10:11]
	s_add_u32 s10, s10, 0x6000
	s_addc_u32 s11, s11, 0
	global_load_dword v175, v133, s[10:11]
	s_add_u32 s10, s10, 0x6000
	s_addc_u32 s11, s11, 0
	global_load_dword v176, v133, s[10:11]
	s_add_u32 s10, s10, 0x6000
	s_addc_u32 s11, s11, 0
	global_load_dword v177, v133, s[10:11]
	s_add_u32 s10, s10, 0x6000
	s_addc_u32 s11, s11, 0
	global_load_dword v178, v133, s[10:11]
	s_add_u32 s10, s10, 0x6000
	s_addc_u32 s11, s11, 0
	global_load_dword v179, v133, s[10:11]
	s_add_u32 s10, s10, 0x6000
	s_addc_u32 s11, s11, 0
	global_load_dword v180, v133, s[10:11]
	s_add_u32 s10, s10, 0x6000
	s_addc_u32 s11, s11, 0
	global_load_dword v181, v133, s[10:11]
	s_add_u32 s10, s10, 0x6000
	s_addc_u32 s11, s11, 0
	ds_read_b128 v[14:17], v13 offset:192
	ds_read_b128 v[18:21], v13 offset:208
	ds_read_b128 v[22:25], v13 offset:4288
	ds_read_b128 v[26:29], v13 offset:4304
	ds_read_b128 v[30:33], v13 offset:8384
	ds_read_b128 v[34:37], v13 offset:8400
	s_waitcnt vmcnt(48)
	s_waitcnt lgkmcnt(0)
	v_fmac_f32_e32 v8, v182, v14
	v_fmac_f32_e32 v9, v182, v22
	v_fmac_f32_e32 v4, v182, v30
	v_fmac_f32_e32 v8, v183, v15
	v_fmac_f32_e32 v9, v183, v23
	v_fmac_f32_e32 v4, v183, v31
	v_fmac_f32_e32 v8, v184, v16
	v_fmac_f32_e32 v9, v184, v24
	v_fmac_f32_e32 v4, v184, v32
	v_fmac_f32_e32 v8, v185, v17
	v_fmac_f32_e32 v9, v185, v25
	v_fmac_f32_e32 v4, v185, v33
	v_fmac_f32_e32 v8, v186, v18
	v_fmac_f32_e32 v9, v186, v26
	v_fmac_f32_e32 v4, v186, v34
	v_fmac_f32_e32 v8, v187, v19
	v_fmac_f32_e32 v9, v187, v27
	v_fmac_f32_e32 v4, v187, v35
	v_fmac_f32_e32 v8, v188, v20
	v_fmac_f32_e32 v9, v188, v28
	v_fmac_f32_e32 v4, v188, v36
	v_fmac_f32_e32 v8, v189, v21
	v_fmac_f32_e32 v9, v189, v29
	v_fmac_f32_e32 v4, v189, v37
	global_load_dword v182, v133, s[10:11]
	s_add_u32 s10, s10, 0x6000
	s_addc_u32 s11, s11, 0
	global_load_dword v183, v133, s[10:11]
	s_add_u32 s10, s10, 0x6000
	s_addc_u32 s11, s11, 0
	global_load_dword v184, v133, s[10:11]
	s_add_u32 s10, s10, 0x6000
	s_addc_u32 s11, s11, 0
	global_load_dword v185, v133, s[10:11]
	s_add_u32 s10, s10, 0x6000
	s_addc_u32 s11, s11, 0
	global_load_dword v186, v133, s[10:11]
	s_add_u32 s10, s10, 0x6000
	s_addc_u32 s11, s11, 0
	global_load_dword v187, v133, s[10:11]
	s_add_u32 s10, s10, 0x6000
	s_addc_u32 s11, s11, 0
	global_load_dword v188, v133, s[10:11]
	s_add_u32 s10, s10, 0x6000
	s_addc_u32 s11, s11, 0
	global_load_dword v189, v133, s[10:11]
	s_add_u32 s10, s10, 0x6000
	s_addc_u32 s11, s11, 0
	ds_read_b128 v[14:17], v13 offset:224
	ds_read_b128 v[18:21], v13 offset:240
	ds_read_b128 v[22:25], v13 offset:4320
	ds_read_b128 v[26:29], v13 offset:4336
	ds_read_b128 v[30:33], v13 offset:8416
	ds_read_b128 v[34:37], v13 offset:8432
	s_waitcnt vmcnt(48)
	s_waitcnt lgkmcnt(0)
	v_fmac_f32_e32 v8, v134, v14
	v_fmac_f32_e32 v9, v134, v22
	v_fmac_f32_e32 v4, v134, v30
	v_fmac_f32_e32 v8, v135, v15
	v_fmac_f32_e32 v9, v135, v23
	v_fmac_f32_e32 v4, v135, v31
	v_fmac_f32_e32 v8, v136, v16
	v_fmac_f32_e32 v9, v136, v24
	v_fmac_f32_e32 v4, v136, v32
	v_fmac_f32_e32 v8, v137, v17
	v_fmac_f32_e32 v9, v137, v25
	v_fmac_f32_e32 v4, v137, v33
	v_fmac_f32_e32 v8, v138, v18
	v_fmac_f32_e32 v9, v138, v26
	v_fmac_f32_e32 v4, v138, v34
	v_fmac_f32_e32 v8, v139, v19
	v_fmac_f32_e32 v9, v139, v27
	v_fmac_f32_e32 v4, v139, v35
	v_fmac_f32_e32 v8, v140, v20
	v_fmac_f32_e32 v9, v140, v28
	v_fmac_f32_e32 v4, v140, v36
	v_fmac_f32_e32 v8, v141, v21
	v_fmac_f32_e32 v9, v141, v29
	v_fmac_f32_e32 v4, v141, v37
	global_load_dword v134, v133, s[10:11]
	s_add_u32 s10, s10, 0x6000
	s_addc_u32 s11, s11, 0
	global_load_dword v135, v133, s[10:11]
	s_add_u32 s10, s10, 0x6000
	s_addc_u32 s11, s11, 0
	global_load_dword v136, v133, s[10:11]
	s_add_u32 s10, s10, 0x6000
	s_addc_u32 s11, s11, 0
	global_load_dword v137, v133, s[10:11]
	s_add_u32 s10, s10, 0x6000
	s_addc_u32 s11, s11, 0
	global_load_dword v138, v133, s[10:11]
	s_add_u32 s10, s10, 0x6000
	s_addc_u32 s11, s11, 0
	global_load_dword v139, v133, s[10:11]
	s_add_u32 s10, s10, 0x6000
	s_addc_u32 s11, s11, 0
	global_load_dword v140, v133, s[10:11]
	s_add_u32 s10, s10, 0x6000
	s_addc_u32 s11, s11, 0
	global_load_dword v141, v133, s[10:11]
	s_add_u32 s10, s10, 0x6000
	s_addc_u32 s11, s11, 0
	ds_read_b128 v[14:17], v13 offset:256
	ds_read_b128 v[18:21], v13 offset:272
	ds_read_b128 v[22:25], v13 offset:4352
	ds_read_b128 v[26:29], v13 offset:4368
	ds_read_b128 v[30:33], v13 offset:8448
	ds_read_b128 v[34:37], v13 offset:8464
	s_waitcnt vmcnt(48)
	s_waitcnt lgkmcnt(0)
	v_fmac_f32_e32 v8, v142, v14
	v_fmac_f32_e32 v9, v142, v22
	v_fmac_f32_e32 v4, v142, v30
	v_fmac_f32_e32 v8, v143, v15
	v_fmac_f32_e32 v9, v143, v23
	v_fmac_f32_e32 v4, v143, v31
	v_fmac_f32_e32 v8, v144, v16
	v_fmac_f32_e32 v9, v144, v24
	v_fmac_f32_e32 v4, v144, v32
	v_fmac_f32_e32 v8, v145, v17
	v_fmac_f32_e32 v9, v145, v25
	v_fmac_f32_e32 v4, v145, v33
	v_fmac_f32_e32 v8, v146, v18
	v_fmac_f32_e32 v9, v146, v26
	v_fmac_f32_e32 v4, v146, v34
	v_fmac_f32_e32 v8, v147, v19
	v_fmac_f32_e32 v9, v147, v27
	v_fmac_f32_e32 v4, v147, v35
	v_fmac_f32_e32 v8, v148, v20
	v_fmac_f32_e32 v9, v148, v28
	v_fmac_f32_e32 v4, v148, v36
	v_fmac_f32_e32 v8, v149, v21
	v_fmac_f32_e32 v9, v149, v29
	v_fmac_f32_e32 v4, v149, v37
	global_load_dword v142, v133, s[10:11]
	s_add_u32 s10, s10, 0x6000
	s_addc_u32 s11, s11, 0
	global_load_dword v143, v133, s[10:11]
	s_add_u32 s10, s10, 0x6000
	s_addc_u32 s11, s11, 0
	global_load_dword v144, v133, s[10:11]
	s_add_u32 s10, s10, 0x6000
	s_addc_u32 s11, s11, 0
	global_load_dword v145, v133, s[10:11]
	s_add_u32 s10, s10, 0x6000
	s_addc_u32 s11, s11, 0
	global_load_dword v146, v133, s[10:11]
	s_add_u32 s10, s10, 0x6000
	s_addc_u32 s11, s11, 0
	global_load_dword v147, v133, s[10:11]
	s_add_u32 s10, s10, 0x6000
	s_addc_u32 s11, s11, 0
	global_load_dword v148, v133, s[10:11]
	s_add_u32 s10, s10, 0x6000
	s_addc_u32 s11, s11, 0
	global_load_dword v149, v133, s[10:11]
	s_add_u32 s10, s10, 0x6000
	s_addc_u32 s11, s11, 0
	ds_read_b128 v[14:17], v13 offset:288
	ds_read_b128 v[18:21], v13 offset:304
	ds_read_b128 v[22:25], v13 offset:4384
	ds_read_b128 v[26:29], v13 offset:4400
	ds_read_b128 v[30:33], v13 offset:8480
	ds_read_b128 v[34:37], v13 offset:8496
	s_waitcnt vmcnt(48)
	s_waitcnt lgkmcnt(0)
	v_fmac_f32_e32 v8, v150, v14
	v_fmac_f32_e32 v9, v150, v22
	v_fmac_f32_e32 v4, v150, v30
	v_fmac_f32_e32 v8, v151, v15
	v_fmac_f32_e32 v9, v151, v23
	v_fmac_f32_e32 v4, v151, v31
	v_fmac_f32_e32 v8, v152, v16
	v_fmac_f32_e32 v9, v152, v24
	v_fmac_f32_e32 v4, v152, v32
	v_fmac_f32_e32 v8, v153, v17
	v_fmac_f32_e32 v9, v153, v25
	v_fmac_f32_e32 v4, v153, v33
	v_fmac_f32_e32 v8, v154, v18
	v_fmac_f32_e32 v9, v154, v26
	v_fmac_f32_e32 v4, v154, v34
	v_fmac_f32_e32 v8, v155, v19
	v_fmac_f32_e32 v9, v155, v27
	v_fmac_f32_e32 v4, v155, v35
	v_fmac_f32_e32 v8, v156, v20
	v_fmac_f32_e32 v9, v156, v28
	v_fmac_f32_e32 v4, v156, v36
	v_fmac_f32_e32 v8, v157, v21
	v_fmac_f32_e32 v9, v157, v29
	v_fmac_f32_e32 v4, v157, v37
	ds_read_b128 v[14:17], v13 offset:320
	ds_read_b128 v[18:21], v13 offset:336
	ds_read_b128 v[22:25], v13 offset:4416
	ds_read_b128 v[26:29], v13 offset:4432
	ds_read_b128 v[30:33], v13 offset:8512
	ds_read_b128 v[34:37], v13 offset:8528
	s_waitcnt vmcnt(40)
	s_waitcnt lgkmcnt(0)
	v_fmac_f32_e32 v8, v158, v14
	v_fmac_f32_e32 v9, v158, v22
	v_fmac_f32_e32 v4, v158, v30
	v_fmac_f32_e32 v8, v159, v15
	v_fmac_f32_e32 v9, v159, v23
	v_fmac_f32_e32 v4, v159, v31
	v_fmac_f32_e32 v8, v160, v16
	v_fmac_f32_e32 v9, v160, v24
	v_fmac_f32_e32 v4, v160, v32
	v_fmac_f32_e32 v8, v161, v17
	v_fmac_f32_e32 v9, v161, v25
	v_fmac_f32_e32 v4, v161, v33
	v_fmac_f32_e32 v8, v162, v18
	v_fmac_f32_e32 v9, v162, v26
	v_fmac_f32_e32 v4, v162, v34
	v_fmac_f32_e32 v8, v163, v19
	v_fmac_f32_e32 v9, v163, v27
	v_fmac_f32_e32 v4, v163, v35
	v_fmac_f32_e32 v8, v164, v20
	v_fmac_f32_e32 v9, v164, v28
	v_fmac_f32_e32 v4, v164, v36
	v_fmac_f32_e32 v8, v165, v21
	v_fmac_f32_e32 v9, v165, v29
	v_fmac_f32_e32 v4, v165, v37
	ds_read_b128 v[14:17], v13 offset:352
	ds_read_b128 v[18:21], v13 offset:368
	ds_read_b128 v[22:25], v13 offset:4448
	ds_read_b128 v[26:29], v13 offset:4464
	ds_read_b128 v[30:33], v13 offset:8544
	ds_read_b128 v[34:37], v13 offset:8560
	s_waitcnt vmcnt(32)
	s_waitcnt lgkmcnt(0)
	v_fmac_f32_e32 v8, v166, v14
	v_fmac_f32_e32 v9, v166, v22
	v_fmac_f32_e32 v4, v166, v30
	v_fmac_f32_e32 v8, v167, v15
	v_fmac_f32_e32 v9, v167, v23
	v_fmac_f32_e32 v4, v167, v31
	v_fmac_f32_e32 v8, v168, v16
	v_fmac_f32_e32 v9, v168, v24
	v_fmac_f32_e32 v4, v168, v32
	v_fmac_f32_e32 v8, v169, v17
	v_fmac_f32_e32 v9, v169, v25
	v_fmac_f32_e32 v4, v169, v33
	v_fmac_f32_e32 v8, v170, v18
	v_fmac_f32_e32 v9, v170, v26
	v_fmac_f32_e32 v4, v170, v34
	v_fmac_f32_e32 v8, v171, v19
	v_fmac_f32_e32 v9, v171, v27
	v_fmac_f32_e32 v4, v171, v35
	v_fmac_f32_e32 v8, v172, v20
	v_fmac_f32_e32 v9, v172, v28
	v_fmac_f32_e32 v4, v172, v36
	v_fmac_f32_e32 v8, v173, v21
	v_fmac_f32_e32 v9, v173, v29
	v_fmac_f32_e32 v4, v173, v37
	ds_read_b128 v[14:17], v13 offset:384
	ds_read_b128 v[18:21], v13 offset:400
	ds_read_b128 v[22:25], v13 offset:4480
	ds_read_b128 v[26:29], v13 offset:4496
	ds_read_b128 v[30:33], v13 offset:8576
	ds_read_b128 v[34:37], v13 offset:8592
	s_waitcnt vmcnt(24)
	s_waitcnt lgkmcnt(0)
	v_fmac_f32_e32 v8, v174, v14
	v_fmac_f32_e32 v9, v174, v22
	v_fmac_f32_e32 v4, v174, v30
	v_fmac_f32_e32 v8, v175, v15
	v_fmac_f32_e32 v9, v175, v23
	v_fmac_f32_e32 v4, v175, v31
	v_fmac_f32_e32 v8, v176, v16
	v_fmac_f32_e32 v9, v176, v24
	v_fmac_f32_e32 v4, v176, v32
	v_fmac_f32_e32 v8, v177, v17
	v_fmac_f32_e32 v9, v177, v25
	v_fmac_f32_e32 v4, v177, v33
	v_fmac_f32_e32 v8, v178, v18
	v_fmac_f32_e32 v9, v178, v26
	v_fmac_f32_e32 v4, v178, v34
	v_fmac_f32_e32 v8, v179, v19
	v_fmac_f32_e32 v9, v179, v27
	v_fmac_f32_e32 v4, v179, v35
	v_fmac_f32_e32 v8, v180, v20
	v_fmac_f32_e32 v9, v180, v28
	v_fmac_f32_e32 v4, v180, v36
	v_fmac_f32_e32 v8, v181, v21
	v_fmac_f32_e32 v9, v181, v29
	v_fmac_f32_e32 v4, v181, v37
	ds_read_b128 v[14:17], v13 offset:416
	ds_read_b128 v[18:21], v13 offset:432
	ds_read_b128 v[22:25], v13 offset:4512
	ds_read_b128 v[26:29], v13 offset:4528
	ds_read_b128 v[30:33], v13 offset:8608
	ds_read_b128 v[34:37], v13 offset:8624
	s_waitcnt vmcnt(16)
	s_waitcnt lgkmcnt(0)
	v_fmac_f32_e32 v8, v182, v14
	v_fmac_f32_e32 v9, v182, v22
	v_fmac_f32_e32 v4, v182, v30
	v_fmac_f32_e32 v8, v183, v15
	v_fmac_f32_e32 v9, v183, v23
	v_fmac_f32_e32 v4, v183, v31
	v_fmac_f32_e32 v8, v184, v16
	v_fmac_f32_e32 v9, v184, v24
	v_fmac_f32_e32 v4, v184, v32
	v_fmac_f32_e32 v8, v185, v17
	v_fmac_f32_e32 v9, v185, v25
	v_fmac_f32_e32 v4, v185, v33
	v_fmac_f32_e32 v8, v186, v18
	v_fmac_f32_e32 v9, v186, v26
	v_fmac_f32_e32 v4, v186, v34
	v_fmac_f32_e32 v8, v187, v19
	v_fmac_f32_e32 v9, v187, v27
	v_fmac_f32_e32 v4, v187, v35
	v_fmac_f32_e32 v8, v188, v20
	v_fmac_f32_e32 v9, v188, v28
	v_fmac_f32_e32 v4, v188, v36
	v_fmac_f32_e32 v8, v189, v21
	v_fmac_f32_e32 v9, v189, v29
	v_fmac_f32_e32 v4, v189, v37
	ds_read_b128 v[14:17], v13 offset:448
	ds_read_b128 v[18:21], v13 offset:464
	ds_read_b128 v[22:25], v13 offset:4544
	ds_read_b128 v[26:29], v13 offset:4560
	ds_read_b128 v[30:33], v13 offset:8640
	ds_read_b128 v[34:37], v13 offset:8656
	s_waitcnt vmcnt(8)
	s_waitcnt lgkmcnt(0)
	v_fmac_f32_e32 v8, v134, v14
	v_fmac_f32_e32 v9, v134, v22
	v_fmac_f32_e32 v4, v134, v30
	v_fmac_f32_e32 v8, v135, v15
	v_fmac_f32_e32 v9, v135, v23
	v_fmac_f32_e32 v4, v135, v31
	v_fmac_f32_e32 v8, v136, v16
	v_fmac_f32_e32 v9, v136, v24
	v_fmac_f32_e32 v4, v136, v32
	v_fmac_f32_e32 v8, v137, v17
	v_fmac_f32_e32 v9, v137, v25
	v_fmac_f32_e32 v4, v137, v33
	v_fmac_f32_e32 v8, v138, v18
	v_fmac_f32_e32 v9, v138, v26
	v_fmac_f32_e32 v4, v138, v34
	v_fmac_f32_e32 v8, v139, v19
	v_fmac_f32_e32 v9, v139, v27
	v_fmac_f32_e32 v4, v139, v35
	v_fmac_f32_e32 v8, v140, v20
	v_fmac_f32_e32 v9, v140, v28
	v_fmac_f32_e32 v4, v140, v36
	v_fmac_f32_e32 v8, v141, v21
	v_fmac_f32_e32 v9, v141, v29
	v_fmac_f32_e32 v4, v141, v37
	ds_read_b128 v[14:17], v13 offset:480
	ds_read_b128 v[18:21], v13 offset:496
	ds_read_b128 v[22:25], v13 offset:4576
	ds_read_b128 v[26:29], v13 offset:4592
	ds_read_b128 v[30:33], v13 offset:8672
	ds_read_b128 v[34:37], v13 offset:8688
	s_waitcnt vmcnt(0)
	s_waitcnt lgkmcnt(0)
	v_fmac_f32_e32 v8, v142, v14
	v_fmac_f32_e32 v9, v142, v22
	v_fmac_f32_e32 v4, v142, v30
	v_fmac_f32_e32 v8, v143, v15
	v_fmac_f32_e32 v9, v143, v23
	v_fmac_f32_e32 v4, v143, v31
	v_fmac_f32_e32 v8, v144, v16
	v_fmac_f32_e32 v9, v144, v24
	v_fmac_f32_e32 v4, v144, v32
	v_fmac_f32_e32 v8, v145, v17
	v_fmac_f32_e32 v9, v145, v25
	v_fmac_f32_e32 v4, v145, v33
	v_fmac_f32_e32 v8, v146, v18
	v_fmac_f32_e32 v9, v146, v26
	v_fmac_f32_e32 v4, v146, v34
	v_fmac_f32_e32 v8, v147, v19
	v_fmac_f32_e32 v9, v147, v27
	v_fmac_f32_e32 v4, v147, v35
	v_fmac_f32_e32 v8, v148, v20
	v_fmac_f32_e32 v9, v148, v28
	v_fmac_f32_e32 v4, v148, v36
	v_fmac_f32_e32 v8, v149, v21
	v_fmac_f32_e32 v9, v149, v29
	v_fmac_f32_e32 v4, v149, v37
	ds_write2st64_b32 v3, v8, v9 offset0:48 offset1:49
	ds_write_b32 v3, v4 offset:12800
	s_waitcnt lgkmcnt(0)
	s_barrier
	s_and_saveexec_b64 s[10:11], s[4:5]
	s_cbranch_execz .LBB0_10
	v_readlane_b32 s36, v255, 19
	v_readlane_b32 s16, v255, 40
	s_and_b64 s[6:7], s[6:7], exec
	v_readlane_b32 s48, v255, 31
	v_readlane_b32 s49, v255, 32
	v_readlane_b32 s30, v255, 54
	v_readlane_b32 s31, v255, 55
	s_cselect_b32 s6, s31, s49
	s_cselect_b32 s7, s30, s48
	v_or_b32_e32 v8, s0, v2
	v_mov_b32_e32 v6, s7
	v_mov_b32_e32 v7, s6
	v_ashrrev_i32_e32 v9, 31, v8
	v_lshl_add_u64 v[6:7], v[8:9], 2, v[6:7]
	global_load_dword v13, v[6:7], off
	ds_read2st64_b32 v[6:7], v11 offset0:48 offset1:51
	ds_read2st64_b32 v[8:9], v11 offset0:54 offset1:57
	ds_read2st64_b32 v[14:15], v11 offset0:60 offset1:63
	ds_read2st64_b32 v[16:17], v11 offset0:66 offset1:69
	v_mad_u64_u32 v[18:19], s[6:7], s1, 3, v[0:1]
	s_waitcnt lgkmcnt(3)
	v_add_f32_e32 v6, 0, v6
	v_add_f32_e32 v6, v6, v7
	s_waitcnt lgkmcnt(2)
	v_add_f32_e32 v6, v6, v8
	v_readlane_b32 s6, v255, 56
	v_add_f32_e32 v6, v6, v9
	v_readlane_b32 s7, v255, 57
	s_waitcnt lgkmcnt(1)
	v_add_f32_e32 v6, v6, v14
	v_add_f32_e32 v6, v6, v15
	v_mov_b64_e32 v[20:21], s[6:7]
	s_ashr_i32 s1, s0, 31
	v_mad_i64_i32 v[18:19], s[6:7], v18, s12, v[20:21]
	s_waitcnt lgkmcnt(0)
	v_add_f32_e32 v6, v6, v16
	v_lshlrev_b32_e32 v4, 2, v2
	v_lshl_add_u64 v[18:19], s[0:1], 2, v[18:19]
	v_add_f32_e32 v6, v6, v17
	v_readlane_b32 s37, v255, 20
	v_readlane_b32 s38, v255, 21
	v_readlane_b32 s39, v255, 22
	v_readlane_b32 s40, v255, 23
	v_readlane_b32 s41, v255, 24
	v_readlane_b32 s42, v255, 25
	v_readlane_b32 s43, v255, 26
	v_readlane_b32 s44, v255, 27
	v_readlane_b32 s45, v255, 28
	v_readlane_b32 s46, v255, 29
	v_readlane_b32 s47, v255, 30
	v_readlane_b32 s50, v255, 33
	v_readlane_b32 s51, v255, 34
	v_readlane_b32 s17, v255, 41
	v_readlane_b32 s18, v255, 42
	v_readlane_b32 s19, v255, 43
	v_readlane_b32 s20, v255, 44
	v_readlane_b32 s21, v255, 45
	v_readlane_b32 s22, v255, 46
	v_readlane_b32 s23, v255, 47
	v_readlane_b32 s24, v255, 48
	v_readlane_b32 s25, v255, 49
	v_readlane_b32 s26, v255, 50
	v_readlane_b32 s27, v255, 51
	v_readlane_b32 s28, v255, 52
	v_readlane_b32 s29, v255, 53
	s_waitcnt vmcnt(0)
	v_add_f32_e32 v8, v6, v13
	v_lshl_add_u64 v[6:7], v[18:19], 0, v[4:5]
	global_store_dword v[6:7], v8, off
	s_branch .LBB0_10

.LBB0_187:
	v_readlane_b32 s8, v255, 40
	s_cmpk_gt_i32 s34, 0x5ff
	v_readlane_b32 s9, v255, 41
	v_readlane_b32 s10, v255, 42
	v_readlane_b32 s11, v255, 43
	s_waitcnt lgkmcnt(0)
	s_barrier
	v_readlane_b32 s12, v255, 44
	v_readlane_b32 s13, v255, 45
	v_readlane_b32 s14, v255, 46
	v_readlane_b32 s15, v255, 47
	v_readlane_b32 s16, v255, 48
	v_readlane_b32 s17, v255, 49
	v_readlane_b32 s18, v255, 50
	v_readlane_b32 s19, v255, 51
	v_readlane_b32 s20, v255, 52
	v_readlane_b32 s21, v255, 53
	v_readlane_b32 s22, v255, 54
	v_readlane_b32 s23, v255, 55
	s_add_i32 s0, s96, 64
	s_and_b32 s0, s0, 0xff
	s_cmp_lt_u32 s0, 0x44
	s_cbranch_scc1 .LBB0_190
	s_and_b32 s4, s96, 7
	s_lshr_b32 s5, s96, 3
	s_movk_i32 s2, 0x600
	s_cmp_lt_u32 s4, 4
	s_cselect_b32 s2, 0x5c0, s2
	s_cselect_b32 s6, 1, 0
	s_sub_i32 s5, s5, s6
	s_lshl_b32 s5, s5, 3
	s_add_i32 s5, s5, s86
	s_lshl_b32 s5, s5, 3
	s_mul_i32 s0, s4, 0x600
	s_add_i32 s7, s0, 0x600
	s_add_i32 s0, s0, s5
	s_ashr_i32 s1, s0, 31
	s_ashr_i32 s3, s2, 31
	s_movk_i32 s4, 0xfff
	v_mov_b32_e32 v129, 0
	v_mov_b32_e32 v186, 0x3727c5ac
	s_movk_i32 s5, 0x7fff
	s_mov_b32 s6, 0xffff0000
.LBB0_189:
	v_mbcnt_lo_u32_b32 v0, -1, 0
	v_mbcnt_hi_u32_b32 v0, -1, v0
	s_nop 0
	v_ashrrev_i32_e32 v2, 3, v0
	v_add_u32_e32 v1, s0, v2
	v_ashrrev_i32_e32 v3, 31, v2
	v_lshl_add_u64 v[130:131], s[0:1], 0, v[2:3]
	v_add_u32_e32 v2, 0xfffff000, v1
	v_ashrrev_i32_e32 v3, 31, v2
	v_lshlrev_b64 v[4:5], 12, v[130:131]
	v_lshlrev_b64 v[2:3], 12, v[2:3]
	v_and_b32_e32 v0, 7, v0
	v_lshlrev_b32_e32 v6, 1, v1
	v_lshl_add_u64 v[4:5], s[8:9], 0, v[4:5]
	v_lshl_add_u64 v[2:3], s[10:11], 0, v[2:3]
	v_cmp_lt_i32_e32 vcc, s4, v1
	v_lshlrev_b32_e32 v128, 4, v0
	v_and_b32_e32 v6, 0xffffe000, v6
	v_cndmask_b32_e32 v3, v5, v3, vcc
	v_cndmask_b32_e32 v2, v4, v2, vcc
	v_cndmask_b32_e32 v1, 0, v6, vcc
	v_lshl_add_u64 v[4:5], v[2:3], 0, v[128:129]
	v_add3_u32 v187, 0, v1, v128
	v_lshlrev_b32_e32 v128, 3, v0
	global_load_dwordx4 v[124:127], v[4:5], off
	global_load_dwordx4 v[120:123], v[4:5], off offset:128
	global_load_dwordx4 v[116:119], v[4:5], off offset:256
	global_load_dwordx4 v[108:111], v[4:5], off offset:384
	global_load_dwordx4 v[112:115], v[4:5], off offset:512
	global_load_dwordx4 v[104:107], v[4:5], off offset:640
	global_load_dwordx4 v[96:99], v[4:5], off offset:768
	global_load_dwordx4 v[100:103], v[4:5], off offset:896
	global_load_dwordx4 v[92:95], v[4:5], off offset:1024
	global_load_dwordx4 v[84:87], v[4:5], off offset:1152
	global_load_dwordx4 v[88:91], v[4:5], off offset:1280
	global_load_dwordx4 v[80:83], v[4:5], off offset:1408
	global_load_dwordx4 v[72:75], v[4:5], off offset:1536
	global_load_dwordx4 v[76:79], v[4:5], off offset:1664
	global_load_dwordx4 v[68:71], v[4:5], off offset:1792
	global_load_dwordx4 v[60:63], v[4:5], off offset:1920
	global_load_dwordx4 v[64:67], v[4:5], off offset:2048
	global_load_dwordx4 v[56:59], v[4:5], off offset:2176
	global_load_dwordx4 v[48:51], v[4:5], off offset:2304
	global_load_dwordx4 v[52:55], v[4:5], off offset:2432
	global_load_dwordx4 v[44:47], v[4:5], off offset:2560
	global_load_dwordx4 v[36:39], v[4:5], off offset:2688
	global_load_dwordx4 v[40:43], v[4:5], off offset:2816
	global_load_dwordx4 v[32:35], v[4:5], off offset:2944
	global_load_dwordx4 v[24:27], v[4:5], off offset:3072
	global_load_dwordx4 v[28:31], v[4:5], off offset:3200
	global_load_dwordx4 v[20:23], v[4:5], off offset:3328
	global_load_dwordx4 v[12:15], v[4:5], off offset:3456
	global_load_dwordx4 v[16:19], v[4:5], off offset:3584
	global_load_dwordx4 v[8:11], v[4:5], off offset:3712
	global_load_dwordx4 v[0:3], v[4:5], off offset:3840
	s_nop 0
	global_load_dwordx4 v[4:7], v[4:5], off offset:3968
	ds_read_b128 v[134:137], v187 offset:4096
	ds_read_b128 v[138:141], v187 offset:4224
	ds_read_b128 v[142:145], v187 offset:4352
	ds_read_b128 v[146:149], v187 offset:4480
	v_lshlrev_b64 v[130:131], 11, v[130:131]
	s_waitcnt lgkmcnt(3)
	v_pk_add_f32 v[132:133], v[136:137], 1.0 op_sel_hi:[1,0]
	s_waitcnt lgkmcnt(2)
	v_pk_add_f32 v[136:137], v[140:141], 1.0 op_sel_hi:[1,0]
	s_waitcnt lgkmcnt(1)
	v_pk_add_f32 v[140:141], v[144:145], 1.0 op_sel_hi:[1,0]
	s_waitcnt lgkmcnt(0)
	v_pk_add_f32 v[144:145], v[148:149], 1.0 op_sel_hi:[1,0]
	v_lshl_add_u64 v[130:131], s[60:61], 0, v[130:131]
	v_lshl_add_u64 v[130:131], v[130:131], 0, v[128:129]
	v_pk_add_f32 v[134:135], v[134:135], 1.0 op_sel_hi:[1,0]
	v_pk_add_f32 v[138:139], v[138:139], 1.0 op_sel_hi:[1,0]
	v_pk_add_f32 v[142:143], v[142:143], 1.0 op_sel_hi:[1,0]
	v_pk_add_f32 v[146:147], v[146:147], 1.0 op_sel_hi:[1,0]
	s_add_u32 s0, s0, s2
	s_addc_u32 s1, s1, s3
	s_cmp_ge_i32 s0, s7
	s_waitcnt vmcnt(31)
	v_mov_b32_e32 v148, v124
	s_waitcnt vmcnt(30)
	v_mov_b32_e32 v149, v120
	v_mov_b32_e32 v150, v125
	v_mov_b32_e32 v151, v121
	v_mov_b32_e32 v152, v126
	v_mov_b32_e32 v153, v122
	v_mov_b32_e32 v154, v127
	v_mov_b32_e32 v155, v123
	s_waitcnt vmcnt(29)
	v_mov_b32_e32 v156, v117
	v_mov_b32_e32 v157, v118
	v_mov_b32_e32 v158, v116
	v_mov_b32_e32 v159, v119
	v_pk_add_f32 v[148:149], v[148:149], v[150:151]
	v_pk_add_f32 v[150:151], v[152:153], v[154:155]
	v_pk_add_f32 v[152:153], v[156:157], v[158:159]
	v_pk_add_f32 v[148:149], v[148:149], v[150:151]
	v_pk_add_f32 v[150:151], v[152:153], v[152:153] op_sel:[0,1] op_sel_hi:[1,0]
	v_add_f32_e32 v148, 0, v148
	s_waitcnt vmcnt(28)
	v_add_f32_e32 v160, v108, v109
	v_add_f32_e32 v162, v110, v111
	s_waitcnt vmcnt(27)
	v_mov_b32_e32 v165, v112
	v_mov_b32_e32 v161, v114
	v_mov_b32_e32 v163, v115
	v_mov_b32_e32 v151, v113
	v_add_f32_e32 v164, v148, v149
	s_waitcnt vmcnt(26)
	v_mov_b32_e32 v166, v105
	v_mov_b32_e32 v167, v106
	v_mov_b32_e32 v168, v104
	v_mov_b32_e32 v169, v107
	v_pk_add_f32 v[154:155], v[160:161], v[162:163]
	v_pk_add_f32 v[148:149], v[164:165], v[150:151]
	v_pk_add_f32 v[156:157], v[166:167], v[168:169]
	v_pk_add_f32 v[148:149], v[148:149], v[154:155]
	v_pk_add_f32 v[152:153], v[156:157], v[156:157] op_sel:[0,1] op_sel_hi:[1,0]
	v_pk_add_f32 v[148:149], v[148:149], v[148:149] op_sel:[0,1] op_sel_hi:[1,0]
	s_waitcnt vmcnt(25)
	v_add_f32_e32 v170, v96, v97
	v_add_f32_e32 v172, v98, v99
	s_waitcnt vmcnt(24)
	v_mov_b32_e32 v171, v102
	v_mov_b32_e32 v173, v103
	v_mov_b32_e32 v153, v101
	v_mov_b32_e32 v149, v100
	s_waitcnt vmcnt(23)
	v_mov_b32_e32 v174, v93
	v_mov_b32_e32 v175, v94
	v_mov_b32_e32 v176, v92
	v_mov_b32_e32 v177, v95
	v_pk_add_f32 v[158:159], v[170:171], v[172:173]
	v_pk_add_f32 v[148:149], v[148:149], v[152:153]
	v_pk_add_f32 v[160:161], v[174:175], v[176:177]
	v_pk_add_f32 v[148:149], v[148:149], v[158:159]
	v_pk_add_f32 v[156:157], v[160:161], v[160:161] op_sel:[0,1] op_sel_hi:[1,0]
	v_pk_add_f32 v[148:149], v[148:149], v[148:149] op_sel:[0,1] op_sel_hi:[1,0]
	s_waitcnt vmcnt(22)
	v_add_f32_e32 v178, v84, v85
	v_add_f32_e32 v180, v86, v87
	s_waitcnt vmcnt(21)
	v_mov_b32_e32 v179, v90
	v_mov_b32_e32 v181, v91
	v_mov_b32_e32 v157, v89
	v_mov_b32_e32 v149, v88
	s_waitcnt vmcnt(20)
	v_mov_b32_e32 v182, v81
	v_mov_b32_e32 v183, v82
	v_mov_b32_e32 v184, v80
	v_mov_b32_e32 v185, v83
	v_pk_add_f32 v[162:163], v[178:179], v[180:181]
	v_pk_add_f32 v[148:149], v[148:149], v[156:157]
	v_pk_add_f32 v[166:167], v[182:183], v[184:185]
	v_pk_add_f32 v[148:149], v[148:149], v[162:163]
	v_pk_add_f32 v[160:161], v[166:167], v[166:167] op_sel:[0,1] op_sel_hi:[1,0]
	v_pk_add_f32 v[148:149], v[148:149], v[148:149] op_sel:[0,1] op_sel_hi:[1,0]
	s_waitcnt vmcnt(19)
	v_add_f32_e32 v188, v72, v73
	v_add_f32_e32 v190, v74, v75
	s_waitcnt vmcnt(18)
	v_mov_b32_e32 v189, v78
	v_mov_b32_e32 v191, v79
	v_mov_b32_e32 v161, v77
	v_mov_b32_e32 v149, v76
	s_waitcnt vmcnt(17)
	v_mov_b32_e32 v192, v69
	v_mov_b32_e32 v193, v70
	v_mov_b32_e32 v194, v68
	v_mov_b32_e32 v195, v71
	v_pk_add_f32 v[168:169], v[188:189], v[190:191]
	v_pk_add_f32 v[148:149], v[148:149], v[160:161]
	v_pk_add_f32 v[170:171], v[192:193], v[194:195]
	v_pk_add_f32 v[148:149], v[148:149], v[168:169]
	v_pk_add_f32 v[166:167], v[170:171], v[170:171] op_sel:[0,1] op_sel_hi:[1,0]
	v_pk_add_f32 v[148:149], v[148:149], v[148:149] op_sel:[0,1] op_sel_hi:[1,0]
	s_waitcnt vmcnt(16)
	v_add_f32_e32 v196, v60, v61
	v_add_f32_e32 v198, v62, v63
	s_waitcnt vmcnt(15)
	v_mov_b32_e32 v197, v66
	v_mov_b32_e32 v199, v67
	v_mov_b32_e32 v167, v65
	v_mov_b32_e32 v149, v64
	s_waitcnt vmcnt(14)
	v_mov_b32_e32 v200, v57
	v_mov_b32_e32 v201, v58
	v_mov_b32_e32 v202, v56
	v_mov_b32_e32 v203, v59
	v_pk_add_f32 v[172:173], v[196:197], v[198:199]
	v_pk_add_f32 v[148:149], v[148:149], v[166:167]
	v_pk_add_f32 v[174:175], v[200:201], v[202:203]
	v_pk_add_f32 v[148:149], v[148:149], v[172:173]
	v_pk_add_f32 v[170:171], v[174:175], v[174:175] op_sel:[0,1] op_sel_hi:[1,0]
	v_pk_add_f32 v[148:149], v[148:149], v[148:149] op_sel:[0,1] op_sel_hi:[1,0]
	s_waitcnt vmcnt(13)
	v_add_f32_e32 v204, v48, v49
	v_add_f32_e32 v206, v50, v51
	s_waitcnt vmcnt(12)
	v_mov_b32_e32 v205, v54
	v_mov_b32_e32 v207, v55
	v_mov_b32_e32 v171, v53
	v_mov_b32_e32 v149, v52
	s_waitcnt vmcnt(11)
	v_mov_b32_e32 v208, v45
	v_mov_b32_e32 v209, v46
	v_mov_b32_e32 v210, v44
	v_mov_b32_e32 v211, v47
	v_pk_add_f32 v[176:177], v[204:205], v[206:207]
	v_pk_add_f32 v[148:149], v[148:149], v[170:171]
	v_pk_add_f32 v[178:179], v[208:209], v[210:211]
	v_pk_add_f32 v[148:149], v[148:149], v[176:177]
	v_pk_add_f32 v[174:175], v[178:179], v[178:179] op_sel:[0,1] op_sel_hi:[1,0]
	v_pk_add_f32 v[148:149], v[148:149], v[148:149] op_sel:[0,1] op_sel_hi:[1,0]
	s_waitcnt vmcnt(10)
	v_add_f32_e32 v212, v36, v37
	v_add_f32_e32 v214, v38, v39
	s_waitcnt vmcnt(9)
	v_mov_b32_e32 v213, v42
	v_mov_b32_e32 v215, v43
	v_mov_b32_e32 v175, v41
	v_mov_b32_e32 v149, v40
	s_waitcnt vmcnt(8)
	v_mov_b32_e32 v216, v33
	v_mov_b32_e32 v217, v34
	v_mov_b32_e32 v218, v32
	v_mov_b32_e32 v219, v35
	v_pk_add_f32 v[180:181], v[212:213], v[214:215]
	v_pk_add_f32 v[148:149], v[148:149], v[174:175]
	v_pk_add_f32 v[182:183], v[216:217], v[218:219]
	v_pk_add_f32 v[148:149], v[148:149], v[180:181]
	v_pk_add_f32 v[178:179], v[182:183], v[182:183] op_sel:[0,1] op_sel_hi:[1,0]
	v_pk_add_f32 v[148:149], v[148:149], v[148:149] op_sel:[0,1] op_sel_hi:[1,0]
	s_waitcnt vmcnt(7)
	v_add_f32_e32 v220, v24, v25
	v_add_f32_e32 v222, v26, v27
	s_waitcnt vmcnt(6)
	v_mov_b32_e32 v221, v30
	v_mov_b32_e32 v223, v31
	v_mov_b32_e32 v179, v29
	v_mov_b32_e32 v149, v28
	s_waitcnt vmcnt(5)
	v_mov_b32_e32 v224, v21
	v_mov_b32_e32 v225, v22
	v_mov_b32_e32 v226, v20
	v_mov_b32_e32 v227, v23
	v_pk_add_f32 v[184:185], v[220:221], v[222:223]
	v_pk_add_f32 v[148:149], v[148:149], v[178:179]
	v_pk_add_f32 v[188:189], v[224:225], v[226:227]
	v_pk_add_f32 v[148:149], v[148:149], v[184:185]
	v_pk_add_f32 v[182:183], v[188:189], v[188:189] op_sel:[0,1] op_sel_hi:[1,0]
	v_pk_add_f32 v[148:149], v[148:149], v[148:149] op_sel:[0,1] op_sel_hi:[1,0]
	s_waitcnt vmcnt(4)
	v_add_f32_e32 v228, v12, v13
	v_add_f32_e32 v230, v14, v15
	s_waitcnt vmcnt(3)
	v_mov_b32_e32 v229, v18
	v_mov_b32_e32 v231, v19
	v_mov_b32_e32 v183, v17
	v_mov_b32_e32 v149, v16
	s_waitcnt vmcnt(2)
	v_mov_b32_e32 v232, v9
	v_mov_b32_e32 v233, v10
	v_mov_b32_e32 v234, v8
	v_mov_b32_e32 v235, v11
	v_pk_add_f32 v[190:191], v[228:229], v[230:231]
	v_pk_add_f32 v[148:149], v[148:149], v[182:183]
	v_pk_add_f32 v[192:193], v[232:233], v[234:235]
	v_pk_add_f32 v[148:149], v[148:149], v[190:191]
	v_pk_add_f32 v[188:189], v[192:193], v[192:193] op_sel:[0,1] op_sel_hi:[1,0]
	v_pk_add_f32 v[148:149], v[148:149], v[148:149] op_sel:[0,1] op_sel_hi:[1,0]
	s_waitcnt vmcnt(1)
	v_add_f32_e32 v236, v0, v1
	v_add_f32_e32 v238, v2, v3
	s_waitcnt vmcnt(0)
	v_mov_b32_e32 v237, v6
	v_mov_b32_e32 v239, v7
	v_mov_b32_e32 v189, v5
	v_mov_b32_e32 v149, v4
	v_pk_add_f32 v[194:195], v[236:237], v[238:239]
	v_pk_add_f32 v[148:149], v[148:149], v[188:189]
	s_nop 0
	v_pk_add_f32 v[148:149], v[148:149], v[194:195]
	s_nop 0
	v_add_f32_e32 v148, v148, v149
	s_nop 1
	v_add_f32_dpp v148, v148, v148 quad_perm:[1,0,3,2] row_mask:0xf bank_mask:0xf bound_ctrl:1
	s_nop 1
	v_add_f32_dpp v148, v148, v148 quad_perm:[2,3,0,1] row_mask:0xf bank_mask:0xf bound_ctrl:1
	s_nop 1
	v_add_f32_dpp v201, v148, v148 row_half_mirror row_mask:0xf bank_mask:0xf bound_ctrl:1
	v_fmamk_f32 v125, v201, 0xba800000, v125
	v_fmamk_f32 v121, v201, 0xba800000, v121
	v_fmamk_f32 v117, v201, 0xba800000, v117
	v_fmamk_f32 v116, v201, 0xba800000, v116
	v_fmamk_f32 v119, v201, 0xba800000, v119
	v_fmac_f32_e32 v118, 0xba800000, v201
	v_fmamk_f32 v69, v201, 0xba800000, v69
	v_fmamk_f32 v68, v201, 0xba800000, v68
	v_fmamk_f32 v71, v201, 0xba800000, v71
	v_fmac_f32_e32 v70, 0xba800000, v201
	v_fmamk_f32 v57, v201, 0xba800000, v57
	v_fmamk_f32 v56, v201, 0xba800000, v56
	v_fmamk_f32 v59, v201, 0xba800000, v59
	v_fmac_f32_e32 v58, 0xba800000, v201
	v_fmamk_f32 v45, v201, 0xba800000, v45
	v_fmamk_f32 v44, v201, 0xba800000, v44
	v_fmamk_f32 v47, v201, 0xba800000, v47
	v_fmac_f32_e32 v46, 0xba800000, v201
	v_fmamk_f32 v33, v201, 0xba800000, v33
	v_fmamk_f32 v32, v201, 0xba800000, v32
	v_fmamk_f32 v35, v201, 0xba800000, v35
	v_fmac_f32_e32 v34, 0xba800000, v201
	v_fmamk_f32 v21, v201, 0xba800000, v21
	v_fmamk_f32 v20, v201, 0xba800000, v20
	v_fmamk_f32 v23, v201, 0xba800000, v23
	v_fmac_f32_e32 v22, 0xba800000, v201
	v_fmac_f32_e32 v124, 0xba800000, v201
	v_fmac_f32_e32 v120, 0xba800000, v201
	v_fmamk_f32 v108, v201, 0xba800000, v108
	v_fmac_f32_e32 v110, 0xba800000, v201
	v_fmamk_f32 v105, v201, 0xba800000, v105
	v_fmamk_f32 v104, v201, 0xba800000, v104
	v_fmamk_f32 v107, v201, 0xba800000, v107
	v_fmac_f32_e32 v106, 0xba800000, v201
	v_fmamk_f32 v93, v201, 0xba800000, v93
	v_fmamk_f32 v92, v201, 0xba800000, v92
	v_fmamk_f32 v95, v201, 0xba800000, v95
	v_fmac_f32_e32 v94, 0xba800000, v201
	v_fmamk_f32 v81, v201, 0xba800000, v81
	v_fmamk_f32 v80, v201, 0xba800000, v80
	v_fmamk_f32 v83, v201, 0xba800000, v83
	v_fmac_f32_e32 v82, 0xba800000, v201
	v_fmamk_f32 v9, v201, 0xba800000, v9
	v_fmamk_f32 v8, v201, 0xba800000, v8
	v_fmamk_f32 v11, v201, 0xba800000, v11
	v_fmac_f32_e32 v10, 0xba800000, v201
	v_mov_b32_e32 v150, v125
	v_mov_b32_e32 v151, v121
	v_pk_mul_f32 v[152:153], v[118:119], v[118:119]
	v_pk_mul_f32 v[154:155], v[116:117], v[116:117]
	v_pk_mul_f32 v[168:169], v[70:71], v[70:71]
	v_pk_mul_f32 v[170:171], v[68:69], v[68:69]
	v_pk_mul_f32 v[172:173], v[58:59], v[58:59]
	v_pk_mul_f32 v[174:175], v[56:57], v[56:57]
	v_pk_mul_f32 v[176:177], v[46:47], v[46:47]
	v_pk_mul_f32 v[178:179], v[44:45], v[44:45]
	v_pk_mul_f32 v[180:181], v[34:35], v[34:35]
	v_pk_mul_f32 v[182:183], v[32:33], v[32:33]
	v_pk_mul_f32 v[184:185], v[22:23], v[22:23]
	v_pk_mul_f32 v[188:189], v[20:21], v[20:21]
	v_fmamk_f32 v109, v201, 0xba800000, v109
	v_fmamk_f32 v111, v201, 0xba800000, v111
	v_mov_b32_e32 v148, v124
	v_mov_b32_e32 v149, v120
	v_pk_mul_f32 v[156:157], v[106:107], v[106:107]
	v_pk_mul_f32 v[158:159], v[104:105], v[104:105]
	v_pk_mul_f32 v[160:161], v[94:95], v[94:95]
	v_pk_mul_f32 v[162:163], v[92:93], v[92:93]
	v_pk_mul_f32 v[164:165], v[82:83], v[82:83]
	v_pk_mul_f32 v[166:167], v[80:81], v[80:81]
	v_pk_mul_f32 v[190:191], v[10:11], v[10:11]
	v_pk_mul_f32 v[192:193], v[8:9], v[8:9]
	v_pk_mov_b32 v[194:195], v[154:155], v[152:153] op_sel:[1,0]
	v_mov_b32_e32 v155, v153
	v_pk_mov_b32 v[196:197], v[170:171], v[168:169] op_sel:[1,0]
	v_mov_b32_e32 v171, v169
	v_pk_mov_b32 v[168:169], v[174:175], v[172:173] op_sel:[1,0]
	v_mov_b32_e32 v175, v173
	v_pk_mov_b32 v[172:173], v[178:179], v[176:177] op_sel:[1,0]
	v_mov_b32_e32 v179, v177
	v_pk_mov_b32 v[176:177], v[182:183], v[180:181] op_sel:[1,0]
	v_mov_b32_e32 v183, v181
	v_pk_mov_b32 v[180:181], v[188:189], v[184:185] op_sel:[1,0]
	v_mov_b32_e32 v189, v185
	v_pk_mul_f32 v[150:151], v[150:151], v[150:151]
	v_mul_f32_e32 v200, v108, v108
	v_mul_f32_e32 v202, v110, v110
	v_fmamk_f32 v127, v201, 0xba800000, v127
	v_fmamk_f32 v123, v201, 0xba800000, v123
	v_fmamk_f32 v113, v201, 0xba800000, v113
	v_fmac_f32_e32 v112, 0xba800000, v201
	v_fmamk_f32 v96, v201, 0xba800000, v96
	v_fmac_f32_e32 v98, 0xba800000, v201
	v_pk_mov_b32 v[152:153], v[158:159], v[156:157] op_sel:[1,0]
	v_mov_b32_e32 v159, v157
	v_pk_mov_b32 v[156:157], v[162:163], v[160:161] op_sel:[1,0]
	v_mov_b32_e32 v163, v161
	v_pk_mov_b32 v[160:161], v[166:167], v[164:165] op_sel:[1,0]
	v_mov_b32_e32 v167, v165
	v_pk_mov_b32 v[184:185], v[192:193], v[190:191] op_sel:[1,0]
	v_mov_b32_e32 v193, v191
	v_pk_fma_f32 v[190:191], v[148:149], v[148:149], v[150:151]
	v_pk_add_f32 v[194:195], v[194:195], v[154:155]
	v_pk_add_f32 v[150:151], v[172:173], v[178:179]
	v_pk_add_f32 v[154:155], v[180:181], v[188:189]
	v_pk_fma_f32 v[178:179], v[108:109], v[108:109], v[200:201] op_sel_hi:[1,1,0]
	v_pk_fma_f32 v[180:181], v[110:111], v[110:111], v[202:203] op_sel_hi:[1,1,0]
	v_fmamk_f32 v126, v201, 0xba800000, v126
	v_fmamk_f32 v122, v201, 0xba800000, v122
	v_fmamk_f32 v97, v201, 0xba800000, v97
	v_fmamk_f32 v99, v201, 0xba800000, v99
	v_mov_b32_e32 v148, v127
	v_mov_b32_e32 v149, v123
	v_mul_f32_e32 v204, v96, v96
	v_pk_add_f32 v[160:161], v[160:161], v[166:167]
	v_mul_f32_e32 v166, v98, v98
	v_mul_f32_e32 v178, v112, v112
	v_mul_f32_e32 v180, v113, v113
	v_fmamk_f32 v101, v201, 0xba800000, v101
	v_fmac_f32_e32 v100, 0xba800000, v201
	v_fmamk_f32 v84, v201, 0xba800000, v84
	v_fmac_f32_e32 v86, 0xba800000, v201
	v_mov_b32_e32 v164, v126
	v_mov_b32_e32 v165, v122
	v_pk_mul_f32 v[148:149], v[148:149], v[148:149]
	v_pk_add_f32 v[162:163], v[156:157], v[162:163]
	v_pk_add_f32 v[156:157], v[184:185], v[192:193]
	v_pk_add_f32 v[192:193], v[178:179], v[180:181]
	v_pk_fma_f32 v[178:179], v[96:97], v[96:97], v[204:205] op_sel_hi:[1,1,0]
	v_pk_fma_f32 v[166:167], v[98:99], v[98:99], v[166:167] op_sel_hi:[1,1,0]
	v_fmamk_f32 v85, v201, 0xba800000, v85
	v_fmamk_f32 v87, v201, 0xba800000, v87
	v_pk_fma_f32 v[198:199], v[164:165], v[164:165], v[148:149]
	v_pk_add_f32 v[164:165], v[152:153], v[158:159]
	v_pk_add_f32 v[158:159], v[196:197], v[170:171]
	v_mul_f32_e32 v170, v84, v84
	v_pk_add_f32 v[148:149], v[168:169], v[174:175]
	v_mul_f32_e32 v168, v86, v86
	v_mul_f32_e32 v178, v100, v100
	v_mul_f32_e32 v166, v101, v101
	v_fmamk_f32 v89, v201, 0xba800000, v89
	v_fmac_f32_e32 v88, 0xba800000, v201
	v_fmamk_f32 v72, v201, 0xba800000, v72
	v_fmac_f32_e32 v74, 0xba800000, v201
	v_pk_add_f32 v[152:153], v[176:177], v[182:183]
	v_pk_add_f32 v[182:183], v[178:179], v[166:167]
	v_pk_fma_f32 v[166:167], v[84:85], v[84:85], v[170:171] op_sel_hi:[1,1,0]
	v_pk_fma_f32 v[168:169], v[86:87], v[86:87], v[168:169] op_sel_hi:[1,1,0]
	v_fmamk_f32 v73, v201, 0xba800000, v73
	v_fmamk_f32 v75, v201, 0xba800000, v75
	v_mul_f32_e32 v172, v72, v72
	v_mul_f32_e32 v174, v74, v74
	v_mul_f32_e32 v166, v88, v88
	v_mul_f32_e32 v168, v89, v89
	v_fmamk_f32 v77, v201, 0xba800000, v77
	v_fmac_f32_e32 v76, 0xba800000, v201
	v_fmamk_f32 v60, v201, 0xba800000, v60
	v_fmac_f32_e32 v62, 0xba800000, v201
	v_pk_add_f32 v[180:181], v[166:167], v[168:169]
	v_pk_fma_f32 v[166:167], v[72:73], v[72:73], v[172:173] op_sel_hi:[1,1,0]
	v_pk_fma_f32 v[170:171], v[74:75], v[74:75], v[174:175] op_sel_hi:[1,1,0]
	v_fmamk_f32 v61, v201, 0xba800000, v61
	v_fmamk_f32 v63, v201, 0xba800000, v63
	v_mul_f32_e32 v176, v60, v60
	v_mul_f32_e32 v184, v62, v62
	v_mul_f32_e32 v166, v76, v76
	v_mul_f32_e32 v170, v77, v77
	v_fmamk_f32 v65, v201, 0xba800000, v65
	v_fmac_f32_e32 v64, 0xba800000, v201
	v_fmamk_f32 v48, v201, 0xba800000, v48
	v_fmac_f32_e32 v50, 0xba800000, v201
	v_fmamk_f32 v36, v201, 0xba800000, v36
	v_fmac_f32_e32 v38, 0xba800000, v201
	v_pk_add_f32 v[178:179], v[166:167], v[170:171]
	v_pk_fma_f32 v[166:167], v[60:61], v[60:61], v[176:177] op_sel_hi:[1,1,0]
	v_pk_fma_f32 v[172:173], v[62:63], v[62:63], v[184:185] op_sel_hi:[1,1,0]
	v_fmamk_f32 v49, v201, 0xba800000, v49
	v_fmamk_f32 v51, v201, 0xba800000, v51
	v_fmamk_f32 v37, v201, 0xba800000, v37
	v_fmamk_f32 v39, v201, 0xba800000, v39
	v_fmamk_f32 v24, v201, 0xba800000, v24
	v_fmac_f32_e32 v26, 0xba800000, v201
	v_pk_add_f32 v[188:189], v[190:191], v[198:199]
	v_mul_f32_e32 v190, v48, v48
	v_mul_f32_e32 v196, v50, v50
	v_mul_f32_e32 v198, v36, v36
	v_mul_f32_e32 v168, v38, v38
	v_mul_f32_e32 v166, v64, v64
	v_mul_f32_e32 v172, v65, v65
	v_fmamk_f32 v53, v201, 0xba800000, v53
	v_fmac_f32_e32 v52, 0xba800000, v201
	v_fmamk_f32 v41, v201, 0xba800000, v41
	v_fmac_f32_e32 v40, 0xba800000, v201
	v_fmamk_f32 v25, v201, 0xba800000, v25
	v_fmamk_f32 v27, v201, 0xba800000, v27
	v_mul_f32_e32 v170, v24, v24
	v_pk_add_f32 v[176:177], v[166:167], v[172:173]
	v_mul_f32_e32 v172, v26, v26
	v_pk_fma_f32 v[166:167], v[48:49], v[48:49], v[190:191] op_sel_hi:[1,1,0]
	v_pk_fma_f32 v[174:175], v[50:51], v[50:51], v[196:197] op_sel_hi:[1,1,0]
	v_pk_fma_f32 v[184:185], v[36:37], v[36:37], v[198:199] op_sel_hi:[1,1,0]
	v_pk_fma_f32 v[168:169], v[38:39], v[38:39], v[168:169] op_sel_hi:[1,1,0]
	v_fmamk_f32 v29, v201, 0xba800000, v29
	v_fmac_f32_e32 v28, 0xba800000, v201
	v_fmamk_f32 v12, v201, 0xba800000, v12
	v_fmac_f32_e32 v14, 0xba800000, v201
	v_mul_f32_e32 v166, v52, v52
	v_mul_f32_e32 v174, v53, v53
	v_mul_f32_e32 v184, v40, v40
	v_mul_f32_e32 v168, v41, v41
	v_pk_fma_f32 v[170:171], v[24:25], v[24:25], v[170:171] op_sel_hi:[1,1,0]
	v_pk_fma_f32 v[172:173], v[26:27], v[26:27], v[172:173] op_sel_hi:[1,1,0]
	v_fmamk_f32 v13, v201, 0xba800000, v13
	v_fmamk_f32 v15, v201, 0xba800000, v15
	v_pk_add_f32 v[166:167], v[166:167], v[174:175]
	v_mul_f32_e32 v174, v12, v12
	v_pk_add_f32 v[168:169], v[184:185], v[168:169]
	v_mul_f32_e32 v184, v14, v14
	v_mul_f32_e32 v170, v28, v28
	v_mul_f32_e32 v172, v29, v29
	v_fmamk_f32 v17, v201, 0xba800000, v17
	v_fmac_f32_e32 v16, 0xba800000, v201
	v_pk_add_f32 v[170:171], v[170:171], v[172:173]
	v_pk_fma_f32 v[172:173], v[12:13], v[12:13], v[174:175] op_sel_hi:[1,1,0]
	v_pk_fma_f32 v[174:175], v[14:15], v[14:15], v[184:185] op_sel_hi:[1,1,0]
	v_fmamk_f32 v0, v201, 0xba800000, v0
	v_fmac_f32_e32 v2, 0xba800000, v201
	v_mul_f32_e32 v172, v16, v16
	v_mul_f32_e32 v174, v17, v17
	v_fmamk_f32 v1, v201, 0xba800000, v1
	v_fmamk_f32 v3, v201, 0xba800000, v3
	v_mul_f32_e32 v190, v0, v0
	v_pk_add_f32 v[172:173], v[172:173], v[174:175]
	v_mul_f32_e32 v174, v2, v2
	v_fmamk_f32 v5, v201, 0xba800000, v5
	v_fmac_f32_e32 v4, 0xba800000, v201
	v_pk_fma_f32 v[184:185], v[0:1], v[0:1], v[190:191] op_sel_hi:[1,1,0]
	v_pk_fma_f32 v[174:175], v[2:3], v[2:3], v[174:175] op_sel_hi:[1,1,0]
	v_mul_f32_e32 v184, v4, v4
	v_mul_f32_e32 v174, v5, v5
	v_fmamk_f32 v115, v201, 0xba800000, v115
	v_fmamk_f32 v114, v201, 0xba800000, v114
	v_pk_add_f32 v[174:175], v[184:185], v[174:175]
	v_pk_add_f32 v[184:185], v[194:195], v[194:195] op_sel_hi:[0,1]
	v_pk_add_f32 v[188:189], v[188:189], v[188:189] op_sel_hi:[0,1]
	v_mul_f32_e32 v184, v114, v114
	v_mul_f32_e32 v188, v115, v115
	v_pk_add_f32 v[184:185], v[184:185], v[188:189]
	v_fmamk_f32 v103, v201, 0xba800000, v103
	v_pk_add_f32 v[184:185], v[192:193], v[184:185]
	v_fmamk_f32 v102, v201, 0xba800000, v102
	v_pk_add_f32 v[164:165], v[164:165], v[164:165] op_sel_hi:[0,1]
	v_pk_add_f32 v[184:185], v[184:185], v[184:185] op_sel_hi:[0,1]
	v_mul_f32_e32 v164, v102, v102
	v_mul_f32_e32 v184, v103, v103
	v_pk_add_f32 v[164:165], v[164:165], v[184:185]
	v_fmamk_f32 v91, v201, 0xba800000, v91
	v_pk_add_f32 v[164:165], v[182:183], v[164:165]
	v_fmamk_f32 v90, v201, 0xba800000, v90
	v_pk_add_f32 v[162:163], v[162:163], v[162:163] op_sel_hi:[0,1]
	v_pk_add_f32 v[164:165], v[164:165], v[164:165] op_sel_hi:[0,1]
	v_mul_f32_e32 v162, v90, v90
	v_mul_f32_e32 v164, v91, v91
	v_pk_add_f32 v[162:163], v[162:163], v[164:165]
	v_fmamk_f32 v79, v201, 0xba800000, v79
	v_pk_add_f32 v[180:181], v[180:181], v[162:163]
	v_fmamk_f32 v78, v201, 0xba800000, v78
	v_pk_add_f32 v[160:161], v[160:161], v[160:161] op_sel_hi:[0,1]
	v_pk_add_f32 v[180:181], v[180:181], v[180:181] op_sel_hi:[0,1]
	v_mul_f32_e32 v160, v78, v78
	v_mul_f32_e32 v180, v79, v79
	v_pk_add_f32 v[160:161], v[160:161], v[180:181]
	v_fmamk_f32 v67, v201, 0xba800000, v67
	v_pk_add_f32 v[160:161], v[178:179], v[160:161]
	v_fmamk_f32 v66, v201, 0xba800000, v66
	v_pk_add_f32 v[158:159], v[158:159], v[158:159] op_sel_hi:[0,1]
	v_pk_add_f32 v[160:161], v[160:161], v[160:161] op_sel_hi:[0,1]
	v_mul_f32_e32 v158, v66, v66
	v_mul_f32_e32 v160, v67, v67
	v_pk_add_f32 v[158:159], v[158:159], v[160:161]
	v_fmamk_f32 v55, v201, 0xba800000, v55
	v_pk_add_f32 v[176:177], v[176:177], v[158:159]
	v_fmamk_f32 v54, v201, 0xba800000, v54
	v_pk_add_f32 v[148:149], v[148:149], v[148:149] op_sel_hi:[0,1]
	v_pk_add_f32 v[176:177], v[176:177], v[176:177] op_sel_hi:[0,1]
	v_mul_f32_e32 v148, v54, v54
	v_mul_f32_e32 v176, v55, v55
	v_pk_add_f32 v[148:149], v[148:149], v[176:177]
	v_fmamk_f32 v43, v201, 0xba800000, v43
	v_pk_add_f32 v[148:149], v[166:167], v[148:149]
	v_fmamk_f32 v42, v201, 0xba800000, v42
	v_pk_add_f32 v[150:151], v[150:151], v[150:151] op_sel_hi:[0,1]
	v_pk_add_f32 v[148:149], v[148:149], v[148:149] op_sel_hi:[0,1]
	v_mul_f32_e32 v150, v42, v42
	v_mul_f32_e32 v148, v43, v43
	v_pk_add_f32 v[148:149], v[150:151], v[148:149]
	v_fmamk_f32 v31, v201, 0xba800000, v31
	v_pk_add_f32 v[148:149], v[168:169], v[148:149]
	v_fmamk_f32 v30, v201, 0xba800000, v30
	v_pk_add_f32 v[152:153], v[152:153], v[152:153] op_sel_hi:[0,1]
	v_pk_add_f32 v[148:149], v[148:149], v[148:149] op_sel_hi:[0,1]
	v_mul_f32_e32 v152, v30, v30
	v_mul_f32_e32 v148, v31, v31
	v_pk_add_f32 v[148:149], v[152:153], v[148:149]
	v_fmamk_f32 v19, v201, 0xba800000, v19
	v_pk_add_f32 v[148:149], v[170:171], v[148:149]
	v_fmamk_f32 v18, v201, 0xba800000, v18
	v_pk_add_f32 v[154:155], v[154:155], v[154:155] op_sel_hi:[0,1]
	v_pk_add_f32 v[148:149], v[148:149], v[148:149] op_sel_hi:[0,1]
	v_mul_f32_e32 v154, v18, v18
	v_mul_f32_e32 v148, v19, v19
	v_pk_add_f32 v[148:149], v[154:155], v[148:149]
	v_fmamk_f32 v7, v201, 0xba800000, v7
	v_pk_add_f32 v[148:149], v[172:173], v[148:149]
	v_fmamk_f32 v6, v201, 0xba800000, v6
	v_pk_add_f32 v[156:157], v[156:157], v[156:157] op_sel_hi:[0,1]
	v_pk_add_f32 v[148:149], v[148:149], v[148:149] op_sel_hi:[0,1]
	v_mul_f32_e32 v156, v6, v6
	v_mul_f32_e32 v148, v7, v7
	v_pk_add_f32 v[148:149], v[156:157], v[148:149]
	ds_read_b128 v[182:185], v187
	ds_read_b128 v[162:165], v187 offset:128
	v_pk_add_f32 v[148:149], v[174:175], v[148:149]
	ds_read_b128 v[178:181], v187 offset:256
	ds_read_b128 v[158:161], v187 offset:384
	v_add_f32_e32 v128, v148, v149
	s_nop 1
	v_add_f32_dpp v128, v128, v128 quad_perm:[1,0,3,2] row_mask:0xf bank_mask:0xf bound_ctrl:1
	s_nop 1
	v_add_f32_dpp v128, v128, v128 quad_perm:[2,3,0,1] row_mask:0xf bank_mask:0xf bound_ctrl:1
	s_nop 1
	v_add_f32_dpp v128, v128, v128 row_half_mirror row_mask:0xf bank_mask:0xf bound_ctrl:1
	v_fmamk_f32 v128, v128, 0x3a800000, v186
	v_rsq_f32_e32 v128, v128
	s_nop 0
	v_pk_mul_f32 v[124:125], v[124:125], v[128:129] op_sel_hi:[1,0]
	v_pk_mul_f32 v[126:127], v[126:127], v[128:129] op_sel_hi:[1,0]
	v_pk_mul_f32 v[120:121], v[120:121], v[128:129] op_sel_hi:[1,0]
	v_pk_mul_f32 v[122:123], v[122:123], v[128:129] op_sel_hi:[1,0]
	v_pk_mul_f32 v[116:117], v[116:117], v[128:129] op_sel_hi:[1,0]
	v_pk_mul_f32 v[118:119], v[118:119], v[128:129] op_sel_hi:[1,0]
	v_pk_mul_f32 v[108:109], v[108:109], v[128:129] op_sel_hi:[1,0]
	v_pk_mul_f32 v[110:111], v[110:111], v[128:129] op_sel_hi:[1,0]
	v_pk_mul_f32 v[194:195], v[80:81], v[128:129] op_sel_hi:[1,0]
	v_pk_mul_f32 v[196:197], v[82:83], v[128:129] op_sel_hi:[1,0]
	v_pk_mul_f32 v[80:81], v[74:75], v[128:129] op_sel_hi:[1,0]
	v_pk_mul_f32 v[74:75], v[76:77], v[128:129] op_sel_hi:[1,0]
	v_pk_mul_f32 v[76:77], v[78:79], v[128:129] op_sel_hi:[1,0]
	v_pk_mul_f32 v[78:79], v[70:71], v[128:129] op_sel_hi:[1,0]
	v_pk_mul_f32 v[70:71], v[60:61], v[128:129] op_sel_hi:[1,0]
	v_pk_mul_f32 v[82:83], v[62:63], v[128:129] op_sel_hi:[1,0]
	v_pk_mul_f32 v[60:61], v[64:65], v[128:129] op_sel_hi:[1,0]
	v_pk_mul_f32 v[62:63], v[66:67], v[128:129] op_sel_hi:[1,0]
	v_pk_mul_f32 v[64:65], v[58:59], v[128:129] op_sel_hi:[1,0]
	v_pk_mul_f32 v[58:59], v[48:49], v[128:129] op_sel_hi:[1,0]
	v_pk_mul_f32 v[66:67], v[50:51], v[128:129] op_sel_hi:[1,0]
	v_pk_mul_f32 v[48:49], v[38:39], v[128:129] op_sel_hi:[1,0]
	v_pk_mul_f32 v[38:39], v[40:41], v[128:129] op_sel_hi:[1,0]
	v_pk_mul_f32 v[40:41], v[32:33], v[128:129] op_sel_hi:[1,0]
	v_pk_mul_f32 v[50:51], v[34:35], v[128:129] op_sel_hi:[1,0]
	v_pk_mul_f32 v[32:33], v[26:27], v[128:129] op_sel_hi:[1,0]
	v_pk_mul_f32 v[26:27], v[28:29], v[128:129] op_sel_hi:[1,0]
	v_pk_mul_f32 v[28:29], v[30:31], v[128:129] op_sel_hi:[1,0]
	v_pk_mul_f32 v[30:31], v[22:23], v[128:129] op_sel_hi:[1,0]
	v_pk_mul_f32 v[22:23], v[12:13], v[128:129] op_sel_hi:[1,0]
	v_pk_mul_f32 v[34:35], v[14:15], v[128:129] op_sel_hi:[1,0]
	v_pk_mul_f32 v[12:13], v[16:17], v[128:129] op_sel_hi:[1,0]
	v_pk_mul_f32 v[14:15], v[18:19], v[128:129] op_sel_hi:[1,0]
	v_pk_mul_f32 v[16:17], v[2:3], v[128:129] op_sel_hi:[1,0]
	v_pk_mul_f32 v[2:3], v[4:5], v[128:129] op_sel_hi:[1,0]
	v_pk_mul_f32 v[4:5], v[6:7], v[128:129] op_sel_hi:[1,0]
	s_waitcnt lgkmcnt(3)
	v_pk_fma_f32 v[6:7], v[132:133], v[126:127], v[184:185]
	v_pk_fma_f32 v[18:19], v[134:135], v[124:125], v[182:183]
	v_pk_mul_f32 v[156:157], v[96:97], v[128:129] op_sel_hi:[1,0]
	v_pk_mul_f32 v[166:167], v[98:99], v[128:129] op_sel_hi:[1,0]
	v_pk_mul_f32 v[172:173], v[92:93], v[128:129] op_sel_hi:[1,0]
	v_pk_mul_f32 v[174:175], v[94:95], v[128:129] op_sel_hi:[1,0]
	v_pk_mul_f32 v[176:177], v[84:85], v[128:129] op_sel_hi:[1,0]
	v_pk_mul_f32 v[188:189], v[86:87], v[128:129] op_sel_hi:[1,0]
	v_pk_mul_f32 v[190:191], v[88:89], v[128:129] op_sel_hi:[1,0]
	v_pk_mul_f32 v[192:193], v[90:91], v[128:129] op_sel_hi:[1,0]
	s_waitcnt lgkmcnt(2)
	v_pk_fma_f32 v[84:85], v[136:137], v[122:123], v[164:165]
	v_pk_fma_f32 v[86:87], v[138:139], v[120:121], v[162:163]
	s_waitcnt lgkmcnt(1)
	v_pk_fma_f32 v[88:89], v[140:141], v[118:119], v[180:181]
	v_pk_fma_f32 v[90:91], v[142:143], v[116:117], v[178:179]
	s_waitcnt lgkmcnt(0)
	v_pk_fma_f32 v[92:93], v[144:145], v[110:111], v[160:161]
	v_pk_fma_f32 v[94:95], v[146:147], v[108:109], v[158:159]
	v_bfe_u32 v96, v18, 16, 1
	v_bfe_u32 v98, v6, 16, 1
	v_pk_mul_f32 v[152:153], v[104:105], v[128:129] op_sel_hi:[1,0]
	v_pk_mul_f32 v[154:155], v[106:107], v[128:129] op_sel_hi:[1,0]
	v_pk_mul_f32 v[168:169], v[100:101], v[128:129] op_sel_hi:[1,0]
	v_pk_mul_f32 v[170:171], v[102:103], v[128:129] op_sel_hi:[1,0]
	v_bfe_u32 v97, v19, 16, 1
	v_bfe_u32 v99, v7, 16, 1
	v_bfe_u32 v100, v86, 16, 1
	v_bfe_u32 v102, v84, 16, 1
	v_bfe_u32 v104, v90, 16, 1
	v_bfe_u32 v106, v88, 16, 1
	v_bfe_u32 v108, v94, 16, 1
	v_bfe_u32 v110, v92, 16, 1
	v_add3_u32 v18, v18, v96, s5
	v_add3_u32 v6, v6, v98, s5
	v_bfe_u32 v101, v87, 16, 1
	v_bfe_u32 v103, v85, 16, 1
	v_bfe_u32 v105, v91, 16, 1
	v_bfe_u32 v107, v89, 16, 1
	v_bfe_u32 v109, v95, 16, 1
	v_bfe_u32 v111, v93, 16, 1
	v_add3_u32 v19, v19, v97, s5
	v_add3_u32 v7, v7, v99, s5
	v_add3_u32 v86, v86, v100, s5
	v_add3_u32 v84, v84, v102, s5
	v_add3_u32 v90, v90, v104, s5
	v_add3_u32 v88, v88, v106, s5
	v_add3_u32 v94, v94, v108, s5
	v_add3_u32 v92, v92, v110, s5
	v_lshrrev_b32_e32 v18, 16, v18
	v_lshrrev_b32_e32 v96, 16, v6
	v_add3_u32 v87, v87, v101, s5
	v_add3_u32 v85, v85, v103, s5
	v_add3_u32 v91, v91, v105, s5
	v_add3_u32 v89, v89, v107, s5
	v_add3_u32 v95, v95, v109, s5
	v_add3_u32 v93, v93, v111, s5
	v_lshrrev_b32_e32 v86, 16, v86
	v_lshrrev_b32_e32 v84, 16, v84
	v_lshrrev_b32_e32 v90, 16, v90
	v_lshrrev_b32_e32 v88, 16, v88
	v_lshrrev_b32_e32 v94, 16, v94
	v_lshrrev_b32_e32 v92, 16, v92
	v_and_or_b32 v6, v19, s6, v18
	v_and_or_b32 v7, v7, s6, v96
	v_and_or_b32 v18, v87, s6, v86
	v_and_or_b32 v19, v85, s6, v84
	v_and_or_b32 v84, v91, s6, v90
	v_and_or_b32 v85, v89, s6, v88
	v_and_or_b32 v86, v95, s6, v94
	v_and_or_b32 v87, v93, s6, v92
	global_store_dwordx2 v[130:131], v[6:7], off
	global_store_dwordx2 v[130:131], v[18:19], off offset:64
	global_store_dwordx2 v[130:131], v[84:85], off offset:128
	global_store_dwordx2 v[130:131], v[86:87], off offset:192
	v_pk_mul_f32 v[148:149], v[112:113], v[128:129] op_sel_hi:[1,0]
	v_pk_mul_f32 v[150:151], v[114:115], v[128:129] op_sel_hi:[1,0]
	ds_read_b128 v[84:87], v187 offset:4608
	ds_read_b128 v[88:91], v187 offset:4736
	ds_read_b128 v[92:95], v187 offset:512
	ds_read_b128 v[96:99], v187 offset:640
	ds_read_b128 v[100:103], v187 offset:4864
	ds_read_b128 v[104:107], v187 offset:4992
	ds_read_b128 v[108:111], v187 offset:768
	ds_read_b128 v[112:115], v187 offset:896
	s_waitcnt lgkmcnt(7)
	v_pk_add_f32 v[6:7], v[86:87], 1.0 op_sel_hi:[1,0]
	v_pk_add_f32 v[18:19], v[84:85], 1.0 op_sel_hi:[1,0]
	s_waitcnt lgkmcnt(6)
	v_pk_add_f32 v[84:85], v[90:91], 1.0 op_sel_hi:[1,0]
	v_pk_add_f32 v[86:87], v[88:89], 1.0 op_sel_hi:[1,0]
	s_waitcnt lgkmcnt(3)
	v_pk_add_f32 v[88:89], v[102:103], 1.0 op_sel_hi:[1,0]
	v_pk_add_f32 v[90:91], v[100:101], 1.0 op_sel_hi:[1,0]
	s_waitcnt lgkmcnt(2)
	v_pk_add_f32 v[100:101], v[106:107], 1.0 op_sel_hi:[1,0]
	v_pk_add_f32 v[102:103], v[104:105], 1.0 op_sel_hi:[1,0]
	v_pk_fma_f32 v[6:7], v[6:7], v[150:151], v[94:95]
	v_pk_fma_f32 v[18:19], v[18:19], v[148:149], v[92:93]
	v_pk_fma_f32 v[84:85], v[84:85], v[154:155], v[98:99]
	v_pk_fma_f32 v[86:87], v[86:87], v[152:153], v[96:97]
	s_waitcnt lgkmcnt(1)
	v_pk_fma_f32 v[88:89], v[88:89], v[166:167], v[110:111]
	v_pk_fma_f32 v[90:91], v[90:91], v[156:157], v[108:109]
	s_waitcnt lgkmcnt(0)
	v_pk_fma_f32 v[92:93], v[100:101], v[170:171], v[114:115]
	v_pk_fma_f32 v[94:95], v[102:103], v[168:169], v[112:113]
	v_bfe_u32 v96, v18, 16, 1
	v_bfe_u32 v98, v6, 16, 1
	v_bfe_u32 v97, v19, 16, 1
	v_bfe_u32 v99, v7, 16, 1
	v_bfe_u32 v100, v86, 16, 1
	v_bfe_u32 v102, v84, 16, 1
	v_bfe_u32 v104, v90, 16, 1
	v_bfe_u32 v106, v88, 16, 1
	v_bfe_u32 v108, v94, 16, 1
	v_bfe_u32 v110, v92, 16, 1
	v_add3_u32 v18, v18, v96, s5
	v_add3_u32 v6, v6, v98, s5
	v_bfe_u32 v101, v87, 16, 1
	v_bfe_u32 v103, v85, 16, 1
	v_bfe_u32 v105, v91, 16, 1
	v_bfe_u32 v107, v89, 16, 1
	v_bfe_u32 v109, v95, 16, 1
	v_bfe_u32 v111, v93, 16, 1
	v_add3_u32 v19, v19, v97, s5
	v_add3_u32 v7, v7, v99, s5
	v_add3_u32 v86, v86, v100, s5
	v_add3_u32 v84, v84, v102, s5
	v_add3_u32 v90, v90, v104, s5
	v_add3_u32 v88, v88, v106, s5
	v_add3_u32 v94, v94, v108, s5
	v_add3_u32 v92, v92, v110, s5
	v_lshrrev_b32_e32 v18, 16, v18
	v_lshrrev_b32_e32 v96, 16, v6
	v_add3_u32 v87, v87, v101, s5
	v_add3_u32 v85, v85, v103, s5
	v_add3_u32 v91, v91, v105, s5
	v_add3_u32 v89, v89, v107, s5
	v_add3_u32 v95, v95, v109, s5
	v_add3_u32 v93, v93, v111, s5
	v_lshrrev_b32_e32 v86, 16, v86
	v_lshrrev_b32_e32 v84, 16, v84
	v_lshrrev_b32_e32 v90, 16, v90
	v_lshrrev_b32_e32 v88, 16, v88
	v_lshrrev_b32_e32 v94, 16, v94
	v_lshrrev_b32_e32 v92, 16, v92
	v_and_or_b32 v6, v19, s6, v18
	v_and_or_b32 v7, v7, s6, v96
	v_and_or_b32 v18, v87, s6, v86
	v_and_or_b32 v19, v85, s6, v84
	v_and_or_b32 v84, v91, s6, v90
	v_and_or_b32 v85, v89, s6, v88
	v_and_or_b32 v86, v95, s6, v94
	v_and_or_b32 v87, v93, s6, v92
	global_store_dwordx2 v[130:131], v[6:7], off offset:256
	global_store_dwordx2 v[130:131], v[18:19], off offset:320
	global_store_dwordx2 v[130:131], v[84:85], off offset:384
	global_store_dwordx2 v[130:131], v[86:87], off offset:448
	ds_read_b128 v[84:87], v187 offset:5120
	ds_read_b128 v[88:91], v187 offset:5248
	ds_read_b128 v[92:95], v187 offset:1024
	ds_read_b128 v[96:99], v187 offset:1152
	ds_read_b128 v[100:103], v187 offset:5376
	ds_read_b128 v[104:107], v187 offset:5504
	ds_read_b128 v[108:111], v187 offset:1280
	ds_read_b128 v[112:115], v187 offset:1408
	s_waitcnt lgkmcnt(7)
	v_pk_add_f32 v[6:7], v[86:87], 1.0 op_sel_hi:[1,0]
	v_pk_add_f32 v[18:19], v[84:85], 1.0 op_sel_hi:[1,0]
	s_waitcnt lgkmcnt(6)
	v_pk_add_f32 v[84:85], v[90:91], 1.0 op_sel_hi:[1,0]
	v_pk_add_f32 v[86:87], v[88:89], 1.0 op_sel_hi:[1,0]
	s_waitcnt lgkmcnt(3)
	v_pk_add_f32 v[88:89], v[102:103], 1.0 op_sel_hi:[1,0]
	v_pk_add_f32 v[90:91], v[100:101], 1.0 op_sel_hi:[1,0]
	s_waitcnt lgkmcnt(2)
	v_pk_add_f32 v[100:101], v[106:107], 1.0 op_sel_hi:[1,0]
	v_pk_add_f32 v[102:103], v[104:105], 1.0 op_sel_hi:[1,0]
	v_pk_fma_f32 v[6:7], v[6:7], v[174:175], v[94:95]
	v_pk_fma_f32 v[18:19], v[18:19], v[172:173], v[92:93]
	v_pk_fma_f32 v[84:85], v[84:85], v[188:189], v[98:99]
	v_pk_fma_f32 v[86:87], v[86:87], v[176:177], v[96:97]
	s_waitcnt lgkmcnt(1)
	v_pk_fma_f32 v[88:89], v[88:89], v[192:193], v[110:111]
	v_pk_fma_f32 v[90:91], v[90:91], v[190:191], v[108:109]
	s_waitcnt lgkmcnt(0)
	v_pk_fma_f32 v[92:93], v[100:101], v[196:197], v[114:115]
	v_pk_fma_f32 v[94:95], v[102:103], v[194:195], v[112:113]
	v_bfe_u32 v96, v18, 16, 1
	v_bfe_u32 v98, v6, 16, 1
	v_bfe_u32 v97, v19, 16, 1
	v_bfe_u32 v99, v7, 16, 1
	v_bfe_u32 v100, v86, 16, 1
	v_bfe_u32 v102, v84, 16, 1
	v_bfe_u32 v104, v90, 16, 1
	v_bfe_u32 v106, v88, 16, 1
	v_bfe_u32 v108, v94, 16, 1
	v_bfe_u32 v110, v92, 16, 1
	v_add3_u32 v18, v18, v96, s5
	v_add3_u32 v6, v6, v98, s5
	v_bfe_u32 v101, v87, 16, 1
	v_bfe_u32 v103, v85, 16, 1
	v_bfe_u32 v105, v91, 16, 1
	v_bfe_u32 v107, v89, 16, 1
	v_bfe_u32 v109, v95, 16, 1
	v_bfe_u32 v111, v93, 16, 1
	v_add3_u32 v19, v19, v97, s5
	v_add3_u32 v7, v7, v99, s5
	v_add3_u32 v86, v86, v100, s5
	v_add3_u32 v84, v84, v102, s5
	v_add3_u32 v90, v90, v104, s5
	v_add3_u32 v88, v88, v106, s5
	v_add3_u32 v94, v94, v108, s5
	v_add3_u32 v92, v92, v110, s5
	v_lshrrev_b32_e32 v18, 16, v18
	v_lshrrev_b32_e32 v96, 16, v6
	v_add3_u32 v87, v87, v101, s5
	v_add3_u32 v85, v85, v103, s5
	v_add3_u32 v91, v91, v105, s5
	v_add3_u32 v89, v89, v107, s5
	v_add3_u32 v95, v95, v109, s5
	v_add3_u32 v93, v93, v111, s5
	v_lshrrev_b32_e32 v86, 16, v86
	v_lshrrev_b32_e32 v84, 16, v84
	v_lshrrev_b32_e32 v90, 16, v90
	v_lshrrev_b32_e32 v88, 16, v88
	v_lshrrev_b32_e32 v94, 16, v94
	v_lshrrev_b32_e32 v92, 16, v92
	v_and_or_b32 v6, v19, s6, v18
	v_and_or_b32 v7, v7, s6, v96
	v_and_or_b32 v18, v87, s6, v86
	v_and_or_b32 v19, v85, s6, v84
	v_and_or_b32 v84, v91, s6, v90
	v_and_or_b32 v85, v89, s6, v88
	v_and_or_b32 v86, v95, s6, v94
	v_and_or_b32 v87, v93, s6, v92
	global_store_dwordx2 v[130:131], v[6:7], off offset:512
	global_store_dwordx2 v[130:131], v[18:19], off offset:576
	global_store_dwordx2 v[130:131], v[84:85], off offset:640
	global_store_dwordx2 v[130:131], v[86:87], off offset:704
	ds_read_b128 v[84:87], v187 offset:5632
	ds_read_b128 v[88:91], v187 offset:5760
	ds_read_b128 v[92:95], v187 offset:1536
	ds_read_b128 v[96:99], v187 offset:1664
	ds_read_b128 v[100:103], v187 offset:5888
	ds_read_b128 v[104:107], v187 offset:6016
	ds_read_b128 v[108:111], v187 offset:1792
	ds_read_b128 v[112:115], v187 offset:1920
	v_pk_mul_f32 v[72:73], v[72:73], v[128:129] op_sel_hi:[1,0]
	s_waitcnt lgkmcnt(7)
	v_pk_add_f32 v[6:7], v[86:87], 1.0 op_sel_hi:[1,0]
	v_pk_add_f32 v[18:19], v[84:85], 1.0 op_sel_hi:[1,0]
	v_pk_mul_f32 v[68:69], v[68:69], v[128:129] op_sel_hi:[1,0]
	s_waitcnt lgkmcnt(6)
	v_pk_add_f32 v[84:85], v[90:91], 1.0 op_sel_hi:[1,0]
	v_pk_add_f32 v[86:87], v[88:89], 1.0 op_sel_hi:[1,0]
	s_waitcnt lgkmcnt(3)
	v_pk_add_f32 v[88:89], v[102:103], 1.0 op_sel_hi:[1,0]
	v_pk_add_f32 v[90:91], v[100:101], 1.0 op_sel_hi:[1,0]
	s_waitcnt lgkmcnt(2)
	v_pk_add_f32 v[100:101], v[106:107], 1.0 op_sel_hi:[1,0]
	v_pk_add_f32 v[102:103], v[104:105], 1.0 op_sel_hi:[1,0]
	v_pk_fma_f32 v[6:7], v[6:7], v[80:81], v[94:95]
	v_pk_fma_f32 v[18:19], v[18:19], v[72:73], v[92:93]
	v_pk_fma_f32 v[72:73], v[84:85], v[76:77], v[98:99]
	v_pk_fma_f32 v[74:75], v[86:87], v[74:75], v[96:97]
	s_waitcnt lgkmcnt(1)
	v_pk_fma_f32 v[76:77], v[88:89], v[78:79], v[110:111]
	v_pk_fma_f32 v[68:69], v[90:91], v[68:69], v[108:109]
	s_waitcnt lgkmcnt(0)
	v_pk_fma_f32 v[78:79], v[82:83], v[100:101], v[114:115]
	v_pk_fma_f32 v[70:71], v[70:71], v[102:103], v[112:113]
	v_bfe_u32 v80, v18, 16, 1
	v_bfe_u32 v82, v6, 16, 1
	v_bfe_u32 v81, v19, 16, 1
	v_bfe_u32 v83, v7, 16, 1
	v_bfe_u32 v84, v74, 16, 1
	v_bfe_u32 v86, v72, 16, 1
	v_bfe_u32 v88, v68, 16, 1
	v_bfe_u32 v90, v76, 16, 1
	v_bfe_u32 v92, v70, 16, 1
	v_bfe_u32 v94, v78, 16, 1
	v_add3_u32 v18, v18, v80, s5
	v_add3_u32 v6, v6, v82, s5
	v_bfe_u32 v85, v75, 16, 1
	v_bfe_u32 v87, v73, 16, 1
	v_bfe_u32 v89, v69, 16, 1
	v_bfe_u32 v91, v77, 16, 1
	v_bfe_u32 v93, v71, 16, 1
	v_bfe_u32 v95, v79, 16, 1
	v_add3_u32 v19, v19, v81, s5
	v_add3_u32 v7, v7, v83, s5
	v_add3_u32 v74, v74, v84, s5
	v_add3_u32 v72, v72, v86, s5
	v_add3_u32 v68, v68, v88, s5
	v_add3_u32 v76, v76, v90, s5
	v_add3_u32 v70, v70, v92, s5
	v_add3_u32 v78, v78, v94, s5
	v_lshrrev_b32_e32 v18, 16, v18
	v_lshrrev_b32_e32 v80, 16, v6
	v_add3_u32 v75, v75, v85, s5
	v_add3_u32 v73, v73, v87, s5
	v_add3_u32 v69, v69, v89, s5
	v_add3_u32 v77, v77, v91, s5
	v_add3_u32 v71, v71, v93, s5
	v_add3_u32 v79, v79, v95, s5
	v_lshrrev_b32_e32 v74, 16, v74
	v_lshrrev_b32_e32 v72, 16, v72
	v_lshrrev_b32_e32 v68, 16, v68
	v_lshrrev_b32_e32 v76, 16, v76
	v_lshrrev_b32_e32 v70, 16, v70
	v_lshrrev_b32_e32 v78, 16, v78
	v_and_or_b32 v6, v19, s6, v18
	v_and_or_b32 v7, v7, s6, v80
	v_and_or_b32 v18, v75, s6, v74
	v_and_or_b32 v19, v73, s6, v72
	v_and_or_b32 v68, v69, s6, v68
	v_and_or_b32 v69, v77, s6, v76
	v_and_or_b32 v70, v71, s6, v70
	v_and_or_b32 v71, v79, s6, v78
	global_store_dwordx2 v[130:131], v[6:7], off offset:768
	global_store_dwordx2 v[130:131], v[18:19], off offset:832
	global_store_dwordx2 v[130:131], v[68:69], off offset:896
	global_store_dwordx2 v[130:131], v[70:71], off offset:960
	ds_read_b128 v[68:71], v187 offset:6144
	ds_read_b128 v[72:75], v187 offset:6272
	ds_read_b128 v[76:79], v187 offset:2048
	ds_read_b128 v[80:83], v187 offset:2176
	ds_read_b128 v[84:87], v187 offset:6400
	ds_read_b128 v[88:91], v187 offset:6528
	ds_read_b128 v[92:95], v187 offset:2304
	ds_read_b128 v[96:99], v187 offset:2432
	s_waitcnt lgkmcnt(7)
	v_pk_add_f32 v[6:7], v[70:71], 1.0 op_sel_hi:[1,0]
	v_pk_add_f32 v[18:19], v[68:69], 1.0 op_sel_hi:[1,0]
	v_pk_mul_f32 v[56:57], v[56:57], v[128:129] op_sel_hi:[1,0]
	v_pk_mul_f32 v[52:53], v[52:53], v[128:129] op_sel_hi:[1,0]
	v_pk_mul_f32 v[54:55], v[54:55], v[128:129] op_sel_hi:[1,0]
	s_waitcnt lgkmcnt(6)
	v_pk_add_f32 v[68:69], v[74:75], 1.0 op_sel_hi:[1,0]
	v_pk_add_f32 v[70:71], v[72:73], 1.0 op_sel_hi:[1,0]
	s_waitcnt lgkmcnt(3)
	v_pk_add_f32 v[72:73], v[86:87], 1.0 op_sel_hi:[1,0]
	v_pk_add_f32 v[74:75], v[84:85], 1.0 op_sel_hi:[1,0]
	s_waitcnt lgkmcnt(2)
	v_pk_add_f32 v[84:85], v[90:91], 1.0 op_sel_hi:[1,0]
	v_pk_add_f32 v[86:87], v[88:89], 1.0 op_sel_hi:[1,0]
	v_pk_fma_f32 v[6:7], v[62:63], v[6:7], v[78:79]
	v_pk_fma_f32 v[18:19], v[60:61], v[18:19], v[76:77]
	v_pk_fma_f32 v[60:61], v[64:65], v[68:69], v[82:83]
	v_pk_fma_f32 v[56:57], v[56:57], v[70:71], v[80:81]
	s_waitcnt lgkmcnt(1)
	v_pk_fma_f32 v[62:63], v[66:67], v[72:73], v[94:95]
	v_pk_fma_f32 v[58:59], v[58:59], v[74:75], v[92:93]
	s_waitcnt lgkmcnt(0)
	v_pk_fma_f32 v[54:55], v[54:55], v[84:85], v[98:99]
	v_pk_fma_f32 v[52:53], v[52:53], v[86:87], v[96:97]
	v_bfe_u32 v64, v18, 16, 1
	v_bfe_u32 v66, v6, 16, 1
	v_bfe_u32 v65, v19, 16, 1
	v_bfe_u32 v67, v7, 16, 1
	v_bfe_u32 v68, v56, 16, 1
	v_bfe_u32 v70, v60, 16, 1
	v_bfe_u32 v72, v58, 16, 1
	v_bfe_u32 v74, v62, 16, 1
	v_bfe_u32 v76, v52, 16, 1
	v_bfe_u32 v77, v53, 16, 1
	v_bfe_u32 v78, v54, 16, 1
	v_add3_u32 v18, v18, v64, s5
	v_add3_u32 v6, v6, v66, s5
	v_bfe_u32 v69, v57, 16, 1
	v_bfe_u32 v71, v61, 16, 1
	v_bfe_u32 v73, v59, 16, 1
	v_bfe_u32 v75, v63, 16, 1
	v_bfe_u32 v79, v55, 16, 1
	v_add3_u32 v19, v19, v65, s5
	v_add3_u32 v7, v7, v67, s5
	v_add3_u32 v56, v56, v68, s5
	v_add3_u32 v60, v60, v70, s5
	v_add3_u32 v58, v58, v72, s5
	v_add3_u32 v62, v62, v74, s5
	v_add3_u32 v52, v52, v76, s5
	v_add3_u32 v64, v53, v77, s5
	v_add3_u32 v53, v54, v78, s5
	v_lshrrev_b32_e32 v18, 16, v18
	v_lshrrev_b32_e32 v54, 16, v6
	v_add3_u32 v57, v57, v69, s5
	v_add3_u32 v61, v61, v71, s5
	v_add3_u32 v59, v59, v73, s5
	v_add3_u32 v63, v63, v75, s5
	v_add3_u32 v55, v55, v79, s5
	v_lshrrev_b32_e32 v56, 16, v56
	v_lshrrev_b32_e32 v60, 16, v60
	v_lshrrev_b32_e32 v58, 16, v58
	v_lshrrev_b32_e32 v62, 16, v62
	v_lshrrev_b32_e32 v65, 16, v52
	v_lshrrev_b32_e32 v66, 16, v53
	v_and_or_b32 v6, v19, s6, v18
	v_and_or_b32 v7, v7, s6, v54
	v_and_or_b32 v18, v57, s6, v56
	v_and_or_b32 v19, v61, s6, v60
	v_and_or_b32 v52, v59, s6, v58
	v_and_or_b32 v53, v63, s6, v62
	v_and_or_b32 v54, v64, s6, v65
	v_and_or_b32 v55, v55, s6, v66
	global_store_dwordx2 v[130:131], v[6:7], off offset:1024
	global_store_dwordx2 v[130:131], v[18:19], off offset:1088
	global_store_dwordx2 v[130:131], v[52:53], off offset:1152
	global_store_dwordx2 v[130:131], v[54:55], off offset:1216
	ds_read_b128 v[52:55], v187 offset:6656
	ds_read_b128 v[56:59], v187 offset:6784
	ds_read_b128 v[60:63], v187 offset:2560
	ds_read_b128 v[64:67], v187 offset:2688
	ds_read_b128 v[68:71], v187 offset:6912
	ds_read_b128 v[72:75], v187 offset:7040
	ds_read_b128 v[76:79], v187 offset:2816
	ds_read_b128 v[80:83], v187 offset:2944
	v_pk_mul_f32 v[44:45], v[44:45], v[128:129] op_sel_hi:[1,0]
	v_pk_mul_f32 v[46:47], v[46:47], v[128:129] op_sel_hi:[1,0]
	s_waitcnt lgkmcnt(7)
	v_pk_add_f32 v[6:7], v[54:55], 1.0 op_sel_hi:[1,0]
	v_pk_add_f32 v[18:19], v[52:53], 1.0 op_sel_hi:[1,0]
	v_pk_mul_f32 v[36:37], v[36:37], v[128:129] op_sel_hi:[1,0]
	v_pk_mul_f32 v[42:43], v[42:43], v[128:129] op_sel_hi:[1,0]
	s_waitcnt lgkmcnt(6)
	v_pk_add_f32 v[52:53], v[58:59], 1.0 op_sel_hi:[1,0]
	v_pk_add_f32 v[54:55], v[56:57], 1.0 op_sel_hi:[1,0]
	s_waitcnt lgkmcnt(3)
	v_pk_add_f32 v[56:57], v[70:71], 1.0 op_sel_hi:[1,0]
	v_pk_add_f32 v[58:59], v[68:69], 1.0 op_sel_hi:[1,0]
	s_waitcnt lgkmcnt(2)
	v_pk_add_f32 v[68:69], v[74:75], 1.0 op_sel_hi:[1,0]
	v_pk_add_f32 v[70:71], v[72:73], 1.0 op_sel_hi:[1,0]
	v_pk_fma_f32 v[6:7], v[46:47], v[6:7], v[62:63]
	v_pk_fma_f32 v[18:19], v[44:45], v[18:19], v[60:61]
	v_pk_fma_f32 v[44:45], v[48:49], v[52:53], v[66:67]
	v_pk_fma_f32 v[36:37], v[36:37], v[54:55], v[64:65]
	s_waitcnt lgkmcnt(1)
	v_pk_fma_f32 v[42:43], v[42:43], v[56:57], v[78:79]
	v_pk_fma_f32 v[38:39], v[38:39], v[58:59], v[76:77]
	s_waitcnt lgkmcnt(0)
	v_pk_fma_f32 v[46:47], v[50:51], v[68:69], v[82:83]
	v_pk_fma_f32 v[40:41], v[40:41], v[70:71], v[80:81]
	v_bfe_u32 v48, v18, 16, 1
	v_bfe_u32 v50, v6, 16, 1
	v_bfe_u32 v49, v19, 16, 1
	v_bfe_u32 v51, v7, 16, 1
	v_bfe_u32 v52, v36, 16, 1
	v_bfe_u32 v54, v44, 16, 1
	v_bfe_u32 v56, v38, 16, 1
	v_bfe_u32 v58, v42, 16, 1
	v_bfe_u32 v60, v40, 16, 1
	v_bfe_u32 v62, v46, 16, 1
	v_add3_u32 v18, v18, v48, s5
	v_add3_u32 v6, v6, v50, s5
	v_bfe_u32 v53, v37, 16, 1
	v_bfe_u32 v55, v45, 16, 1
	v_bfe_u32 v57, v39, 16, 1
	v_bfe_u32 v59, v43, 16, 1
	v_bfe_u32 v61, v41, 16, 1
	v_bfe_u32 v63, v47, 16, 1
	v_add3_u32 v19, v19, v49, s5
	v_add3_u32 v7, v7, v51, s5
	v_add3_u32 v36, v36, v52, s5
	v_add3_u32 v44, v44, v54, s5
	v_add3_u32 v38, v38, v56, s5
	v_add3_u32 v42, v42, v58, s5
	v_add3_u32 v40, v40, v60, s5
	v_add3_u32 v46, v46, v62, s5
	v_lshrrev_b32_e32 v18, 16, v18
	v_lshrrev_b32_e32 v48, 16, v6
	v_add3_u32 v37, v37, v53, s5
	v_add3_u32 v45, v45, v55, s5
	v_add3_u32 v39, v39, v57, s5
	v_add3_u32 v43, v43, v59, s5
	v_add3_u32 v41, v41, v61, s5
	v_add3_u32 v47, v47, v63, s5
	v_lshrrev_b32_e32 v36, 16, v36
	v_lshrrev_b32_e32 v44, 16, v44
	v_lshrrev_b32_e32 v38, 16, v38
	v_lshrrev_b32_e32 v42, 16, v42
	v_lshrrev_b32_e32 v40, 16, v40
	v_lshrrev_b32_e32 v46, 16, v46
	v_and_or_b32 v6, v19, s6, v18
	v_and_or_b32 v7, v7, s6, v48
	v_and_or_b32 v18, v37, s6, v36
	v_and_or_b32 v19, v45, s6, v44
	v_and_or_b32 v36, v39, s6, v38
	v_and_or_b32 v37, v43, s6, v42
	v_and_or_b32 v38, v41, s6, v40
	v_and_or_b32 v39, v47, s6, v46
	global_store_dwordx2 v[130:131], v[6:7], off offset:1280
	global_store_dwordx2 v[130:131], v[18:19], off offset:1344
	global_store_dwordx2 v[130:131], v[36:37], off offset:1408
	global_store_dwordx2 v[130:131], v[38:39], off offset:1472
	ds_read_b128 v[36:39], v187 offset:7168
	ds_read_b128 v[40:43], v187 offset:7296
	ds_read_b128 v[44:47], v187 offset:3072
	ds_read_b128 v[48:51], v187 offset:3200
	ds_read_b128 v[52:55], v187 offset:7424
	ds_read_b128 v[56:59], v187 offset:7552
	ds_read_b128 v[60:63], v187 offset:3328
	ds_read_b128 v[64:67], v187 offset:3456
	v_pk_mul_f32 v[24:25], v[24:25], v[128:129] op_sel_hi:[1,0]
	s_waitcnt lgkmcnt(7)
	v_pk_add_f32 v[6:7], v[38:39], 1.0 op_sel_hi:[1,0]
	v_pk_add_f32 v[18:19], v[36:37], 1.0 op_sel_hi:[1,0]
	v_pk_mul_f32 v[20:21], v[20:21], v[128:129] op_sel_hi:[1,0]
	s_waitcnt lgkmcnt(6)
	v_pk_add_f32 v[36:37], v[42:43], 1.0 op_sel_hi:[1,0]
	v_pk_add_f32 v[38:39], v[40:41], 1.0 op_sel_hi:[1,0]
	s_waitcnt lgkmcnt(3)
	v_pk_add_f32 v[40:41], v[54:55], 1.0 op_sel_hi:[1,0]
	v_pk_add_f32 v[42:43], v[52:53], 1.0 op_sel_hi:[1,0]
	s_waitcnt lgkmcnt(2)
	v_pk_add_f32 v[52:53], v[58:59], 1.0 op_sel_hi:[1,0]
	v_pk_add_f32 v[54:55], v[56:57], 1.0 op_sel_hi:[1,0]
	v_pk_fma_f32 v[6:7], v[32:33], v[6:7], v[46:47]
	v_pk_fma_f32 v[18:19], v[24:25], v[18:19], v[44:45]
	v_pk_fma_f32 v[24:25], v[28:29], v[36:37], v[50:51]
	v_pk_fma_f32 v[26:27], v[26:27], v[38:39], v[48:49]
	s_waitcnt lgkmcnt(1)
	v_pk_fma_f32 v[28:29], v[30:31], v[40:41], v[62:63]
	v_pk_fma_f32 v[20:21], v[20:21], v[42:43], v[60:61]
	s_waitcnt lgkmcnt(0)
	v_pk_fma_f32 v[30:31], v[34:35], v[52:53], v[66:67]
	v_pk_fma_f32 v[22:23], v[22:23], v[54:55], v[64:65]
	v_bfe_u32 v32, v18, 16, 1
	v_bfe_u32 v34, v6, 16, 1
	v_bfe_u32 v33, v19, 16, 1
	v_bfe_u32 v35, v7, 16, 1
	v_bfe_u32 v36, v26, 16, 1
	v_bfe_u32 v38, v24, 16, 1
	v_bfe_u32 v40, v20, 16, 1
	v_bfe_u32 v42, v28, 16, 1
	v_bfe_u32 v44, v22, 16, 1
	v_bfe_u32 v46, v30, 16, 1
	v_add3_u32 v18, v18, v32, s5
	v_add3_u32 v6, v6, v34, s5
	v_bfe_u32 v37, v27, 16, 1
	v_bfe_u32 v39, v25, 16, 1
	v_bfe_u32 v41, v21, 16, 1
	v_bfe_u32 v43, v29, 16, 1
	v_bfe_u32 v45, v23, 16, 1
	v_bfe_u32 v47, v31, 16, 1
	v_add3_u32 v19, v19, v33, s5
	v_add3_u32 v7, v7, v35, s5
	v_add3_u32 v26, v26, v36, s5
	v_add3_u32 v24, v24, v38, s5
	v_add3_u32 v20, v20, v40, s5
	v_add3_u32 v28, v28, v42, s5
	v_add3_u32 v22, v22, v44, s5
	v_add3_u32 v30, v30, v46, s5
	v_lshrrev_b32_e32 v18, 16, v18
	v_lshrrev_b32_e32 v32, 16, v6
	v_add3_u32 v27, v27, v37, s5
	v_add3_u32 v25, v25, v39, s5
	v_add3_u32 v21, v21, v41, s5
	v_add3_u32 v29, v29, v43, s5
	v_add3_u32 v23, v23, v45, s5
	v_add3_u32 v31, v31, v47, s5
	v_lshrrev_b32_e32 v26, 16, v26
	v_lshrrev_b32_e32 v24, 16, v24
	v_lshrrev_b32_e32 v20, 16, v20
	v_lshrrev_b32_e32 v28, 16, v28
	v_lshrrev_b32_e32 v22, 16, v22
	v_lshrrev_b32_e32 v30, 16, v30
	v_and_or_b32 v6, v19, s6, v18
	v_and_or_b32 v7, v7, s6, v32
	v_and_or_b32 v18, v27, s6, v26
	v_and_or_b32 v19, v25, s6, v24
	v_and_or_b32 v20, v21, s6, v20
	v_and_or_b32 v21, v29, s6, v28
	v_and_or_b32 v22, v23, s6, v22
	v_and_or_b32 v23, v31, s6, v30
	global_store_dwordx2 v[130:131], v[6:7], off offset:1536
	global_store_dwordx2 v[130:131], v[18:19], off offset:1600
	global_store_dwordx2 v[130:131], v[20:21], off offset:1664
	global_store_dwordx2 v[130:131], v[22:23], off offset:1728
	ds_read_b128 v[18:21], v187 offset:7680
	ds_read_b128 v[22:25], v187 offset:7808
	ds_read_b128 v[26:29], v187 offset:3584
	ds_read_b128 v[30:33], v187 offset:3712
	ds_read_b128 v[34:37], v187 offset:7936
	ds_read_b128 v[38:41], v187 offset:8064
	ds_read_b128 v[42:45], v187 offset:3840
	ds_read_b128 v[46:49], v187 offset:3968
	s_waitcnt lgkmcnt(7)
	v_pk_add_f32 v[6:7], v[20:21], 1.0 op_sel_hi:[1,0]
	v_pk_add_f32 v[18:19], v[18:19], 1.0 op_sel_hi:[1,0]
	v_pk_mul_f32 v[8:9], v[8:9], v[128:129] op_sel_hi:[1,0]
	v_pk_mul_f32 v[10:11], v[10:11], v[128:129] op_sel_hi:[1,0]
	v_pk_mul_f32 v[0:1], v[0:1], v[128:129] op_sel_hi:[1,0]
	s_waitcnt lgkmcnt(6)
	v_pk_add_f32 v[20:21], v[24:25], 1.0 op_sel_hi:[1,0]
	v_pk_add_f32 v[22:23], v[22:23], 1.0 op_sel_hi:[1,0]
	s_waitcnt lgkmcnt(3)
	v_pk_add_f32 v[24:25], v[36:37], 1.0 op_sel_hi:[1,0]
	v_pk_add_f32 v[34:35], v[34:35], 1.0 op_sel_hi:[1,0]
	s_waitcnt lgkmcnt(2)
	v_pk_add_f32 v[36:37], v[40:41], 1.0 op_sel_hi:[1,0]
	v_pk_add_f32 v[38:39], v[38:39], 1.0 op_sel_hi:[1,0]
	v_pk_fma_f32 v[6:7], v[14:15], v[6:7], v[28:29]
	v_pk_fma_f32 v[12:13], v[12:13], v[18:19], v[26:27]
	v_pk_fma_f32 v[10:11], v[10:11], v[20:21], v[32:33]
	v_pk_fma_f32 v[8:9], v[8:9], v[22:23], v[30:31]
	s_waitcnt lgkmcnt(1)
	v_pk_fma_f32 v[14:15], v[16:17], v[24:25], v[44:45]
	v_pk_fma_f32 v[0:1], v[0:1], v[34:35], v[42:43]
	s_waitcnt lgkmcnt(0)
	v_pk_fma_f32 v[4:5], v[4:5], v[36:37], v[48:49]
	v_pk_fma_f32 v[2:3], v[2:3], v[38:39], v[46:47]
	v_bfe_u32 v16, v12, 16, 1
	v_bfe_u32 v18, v6, 16, 1
	v_bfe_u32 v17, v13, 16, 1
	v_bfe_u32 v19, v7, 16, 1
	v_bfe_u32 v20, v8, 16, 1
	v_bfe_u32 v22, v10, 16, 1
	v_bfe_u32 v24, v0, 16, 1
	v_bfe_u32 v25, v1, 16, 1
	v_bfe_u32 v26, v14, 16, 1
	v_bfe_u32 v27, v15, 16, 1
	v_bfe_u32 v28, v2, 16, 1
	v_bfe_u32 v29, v3, 16, 1
	v_bfe_u32 v30, v4, 16, 1
	v_bfe_u32 v31, v5, 16, 1
	v_add3_u32 v12, v12, v16, s5
	v_add3_u32 v6, v6, v18, s5
	v_bfe_u32 v21, v9, 16, 1
	v_bfe_u32 v23, v11, 16, 1
	v_add3_u32 v13, v13, v17, s5
	v_add3_u32 v7, v7, v19, s5
	v_add3_u32 v8, v8, v20, s5
	v_add3_u32 v10, v10, v22, s5
	v_add3_u32 v0, v0, v24, s5
	v_add3_u32 v16, v1, v25, s5
	v_add3_u32 v1, v14, v26, s5
	v_add3_u32 v14, v15, v27, s5
	v_add3_u32 v2, v2, v28, s5
	v_add3_u32 v15, v3, v29, s5
	v_add3_u32 v3, v4, v30, s5
	v_add3_u32 v17, v5, v31, s5
	v_lshrrev_b32_e32 v4, 16, v12
	v_lshrrev_b32_e32 v5, 16, v6
	v_add3_u32 v9, v9, v21, s5
	v_add3_u32 v11, v11, v23, s5
	v_lshrrev_b32_e32 v6, 16, v8
	v_lshrrev_b32_e32 v8, 16, v10
	v_lshrrev_b32_e32 v10, 16, v0
	v_lshrrev_b32_e32 v12, 16, v1
	v_lshrrev_b32_e32 v18, 16, v2
	v_lshrrev_b32_e32 v19, 16, v3
	v_and_or_b32 v0, v13, s6, v4
	v_and_or_b32 v1, v7, s6, v5
	v_and_or_b32 v2, v9, s6, v6
	v_and_or_b32 v3, v11, s6, v8
	v_and_or_b32 v4, v16, s6, v10
	v_and_or_b32 v5, v14, s6, v12
	v_and_or_b32 v6, v15, s6, v18
	v_and_or_b32 v7, v17, s6, v19
	global_store_dwordx2 v[130:131], v[0:1], off offset:1792
	global_store_dwordx2 v[130:131], v[2:3], off offset:1856
	global_store_dwordx2 v[130:131], v[4:5], off offset:1920
	global_store_dwordx2 v[130:131], v[6:7], off offset:1984
	s_cbranch_scc0 .LBB0_189
